# loop-carried scalar updates of the GEMM K-loops moved from after the last barrier to before the last load-segment wait
# speedup vs baseline: 1.0029x; 1.0029x over previous
.LBB0_67:
	s_add_u32 s34, s6, 0xfff80080
	s_addc_u32 s35, s7, -1
	s_add_i32 s53, 0, 0x10000
	s_cmp_eq_u32 s52, 28
	s_cselect_b32 s37, s25, s35
	s_cselect_b32 s36, s29, s34
	s_cselect_b32 s35, s23, s51
	s_cselect_b32 s34, s49, s50
	s_add_i32 s56, 0, 0x14000
	v_add_u32_e32 v142, s53, v187
	v_add_u32_e32 v158, s56, v187
	ds_read_b128 v[130:133], v142
	ds_read_b128 v[134:137], v142 offset:1024
	ds_read_b128 v[138:141], v142 offset:2048
	ds_read_b128 v[142:145], v142 offset:3072
	ds_read_b128 v[146:149], v158
	ds_read_b128 v[150:153], v158 offset:1024
	ds_read_b128 v[154:157], v158 offset:2048
	ds_read_b128 v[158:161], v158 offset:3072
	v_lshl_add_u64 v[184:185], s[6:7], 0, v[168:169]
	s_add_i32 m0, s43, 0xc000
	ds_read_b128 v[172:175], v199
	ds_read_b128 v[178:181], v199 offset:1024
	ds_read_b128 v[188:191], v199 offset:2048
	ds_read_b128 v[200:203], v199 offset:3072
	ds_read_b128 v[204:207], v199 offset:4096
	ds_read_b128 v[216:219], v199 offset:5120
	ds_read_b128 v[220:223], v199 offset:6144
	ds_read_b128 v[224:227], v199 offset:7168
	global_load_lds_dwordx4 v[184:185], off
	v_lshl_add_u64 v[184:185], s[6:7], 0, v[170:171]
	s_add_i32 m0, s43, 0xe000
	s_nop 0
	global_load_lds_dwordx4 v[184:185], off
	s_waitcnt vmcnt(8) lgkmcnt(0)
	s_barrier
	s_setprio 1
	v_mfma_f32_16x16x32_bf16 v[126:129], v[130:133], v[172:175], v[126:129]
	v_mfma_f32_16x16x32_bf16 v[122:125], v[138:141], v[172:175], v[122:125]
	v_mfma_f32_16x16x32_bf16 v[110:113], v[130:133], v[188:191], v[110:113]
	v_mfma_f32_16x16x32_bf16 v[106:109], v[138:141], v[188:191], v[106:109]
	v_mfma_f32_16x16x32_bf16 v[98:101], v[130:133], v[204:207], v[98:101]
	v_mfma_f32_16x16x32_bf16 v[90:93], v[138:141], v[204:207], v[90:93]
	v_mfma_f32_16x16x32_bf16 v[82:85], v[130:133], v[220:223], v[82:85]
	v_mfma_f32_16x16x32_bf16 v[74:77], v[138:141], v[220:223], v[74:77]
	v_mfma_f32_16x16x32_bf16 v[126:129], v[134:137], v[178:181], v[126:129]
	v_mfma_f32_16x16x32_bf16 v[122:125], v[142:145], v[178:181], v[122:125]
	v_mfma_f32_16x16x32_bf16 v[110:113], v[134:137], v[200:203], v[110:113]
	v_mfma_f32_16x16x32_bf16 v[106:109], v[142:145], v[200:203], v[106:109]
	v_mfma_f32_16x16x32_bf16 v[98:101], v[134:137], v[216:219], v[98:101]
	v_mfma_f32_16x16x32_bf16 v[90:93], v[142:145], v[216:219], v[90:93]
	v_mfma_f32_16x16x32_bf16 v[82:85], v[134:137], v[224:227], v[82:85]
	v_mfma_f32_16x16x32_bf16 v[74:77], v[142:145], v[224:227], v[74:77]
	v_mfma_f32_16x16x32_bf16 v[118:121], v[146:149], v[172:175], v[118:121]
	v_mfma_f32_16x16x32_bf16 v[114:117], v[154:157], v[172:175], v[114:117]
	v_mfma_f32_16x16x32_bf16 v[102:105], v[146:149], v[188:191], v[102:105]
	v_mfma_f32_16x16x32_bf16 v[94:97], v[154:157], v[188:191], v[94:97]
	v_mfma_f32_16x16x32_bf16 v[86:89], v[146:149], v[204:207], v[86:89]
	v_mfma_f32_16x16x32_bf16 v[78:81], v[154:157], v[204:207], v[78:81]
	v_mfma_f32_16x16x32_bf16 v[70:73], v[146:149], v[220:223], v[70:73]
	v_mfma_f32_16x16x32_bf16 v[66:69], v[154:157], v[220:223], v[66:69]
	v_mfma_f32_16x16x32_bf16 v[118:121], v[150:153], v[178:181], v[118:121]
	v_mfma_f32_16x16x32_bf16 v[114:117], v[158:161], v[178:181], v[114:117]
	v_mfma_f32_16x16x32_bf16 v[102:105], v[150:153], v[200:203], v[102:105]
	v_mfma_f32_16x16x32_bf16 v[94:97], v[158:161], v[200:203], v[94:97]
	v_mfma_f32_16x16x32_bf16 v[86:89], v[150:153], v[216:219], v[86:89]
	v_mfma_f32_16x16x32_bf16 v[78:81], v[158:161], v[216:219], v[78:81]
	v_mfma_f32_16x16x32_bf16 v[70:73], v[150:153], v[224:227], v[70:73]
	v_mfma_f32_16x16x32_bf16 v[66:69], v[158:161], v[224:227], v[66:69]
	s_setprio 0
	s_barrier
	s_add_i32 s53, s53, s42
	v_lshl_add_u64 v[184:185], s[34:35], 0, v[210:211]
	s_mov_b32 m0, s53
	ds_read_b128 v[172:175], v199 offset:16384
	ds_read_b128 v[178:181], v199 offset:17408
	ds_read_b128 v[188:191], v199 offset:18432
	ds_read_b128 v[200:203], v199 offset:19456
	ds_read_b128 v[204:207], v199 offset:20480
	ds_read_b128 v[216:219], v199 offset:21504
	ds_read_b128 v[220:223], v199 offset:22528
	ds_read_b128 v[224:227], v199 offset:23552
	global_load_lds_dwordx4 v[184:185], off
	s_add_i32 m0, s53, 0x2000
	s_add_u32 s54, s34, 0x80000
	v_lshl_add_u64 v[192:193], s[34:35], 0, v[162:163]
	s_addc_u32 s55, s35, 0
	s_add_i32 s53, s56, s42
	global_load_lds_dwordx4 v[192:193], off
	v_lshl_add_u64 v[196:197], s[54:55], 0, v[210:211]
	s_mov_b32 m0, s53
	v_lshl_add_u64 v[208:209], s[36:37], 0, v[164:165]
	global_load_lds_dwordx4 v[196:197], off
	v_lshl_add_u64 v[196:197], s[54:55], 0, v[162:163]
	s_add_i32 m0, s53, 0x2000
	s_nop 0
	global_load_lds_dwordx4 v[196:197], off
	v_lshl_add_u64 v[196:197], s[36:37], 0, v[166:167]
	s_mov_b32 m0, s43
	s_nop 0
	global_load_lds_dwordx4 v[196:197], off
	s_mov_b32 m0, s44
	s_nop 0
	global_load_lds_dwordx4 v[208:209], off
	s_waitcnt vmcnt(8) lgkmcnt(0)
	s_barrier
	s_setprio 1
	v_mfma_f32_16x16x32_bf16 v[62:65], v[130:133], v[172:175], v[62:65]
	v_mfma_f32_16x16x32_bf16 v[58:61], v[138:141], v[172:175], v[58:61]
	v_mfma_f32_16x16x32_bf16 v[50:53], v[130:133], v[188:191], v[50:53]
	v_mfma_f32_16x16x32_bf16 v[42:45], v[138:141], v[188:191], v[42:45]
	v_mfma_f32_16x16x32_bf16 v[34:37], v[130:133], v[204:207], v[34:37]
	v_mfma_f32_16x16x32_bf16 v[26:29], v[138:141], v[204:207], v[26:29]
	v_mfma_f32_16x16x32_bf16 v[14:17], v[130:133], v[220:223], v[14:17]
	v_mfma_f32_16x16x32_bf16 v[10:13], v[138:141], v[220:223], v[10:13]
	v_mfma_f32_16x16x32_bf16 v[62:65], v[134:137], v[178:181], v[62:65]
	v_mfma_f32_16x16x32_bf16 v[58:61], v[142:145], v[178:181], v[58:61]
	v_mfma_f32_16x16x32_bf16 v[50:53], v[134:137], v[200:203], v[50:53]
	v_mfma_f32_16x16x32_bf16 v[42:45], v[142:145], v[200:203], v[42:45]
	v_mfma_f32_16x16x32_bf16 v[34:37], v[134:137], v[216:219], v[34:37]
	v_mfma_f32_16x16x32_bf16 v[26:29], v[142:145], v[216:219], v[26:29]
	v_mfma_f32_16x16x32_bf16 v[14:17], v[134:137], v[224:227], v[14:17]
	v_mfma_f32_16x16x32_bf16 v[10:13], v[142:145], v[224:227], v[10:13]
	v_mfma_f32_16x16x32_bf16 v[54:57], v[146:149], v[172:175], v[54:57]
	v_mfma_f32_16x16x32_bf16 v[46:49], v[154:157], v[172:175], v[46:49]
	v_mfma_f32_16x16x32_bf16 v[38:41], v[146:149], v[188:191], v[38:41]
	v_mfma_f32_16x16x32_bf16 v[30:33], v[154:157], v[188:191], v[30:33]
	v_mfma_f32_16x16x32_bf16 v[22:25], v[146:149], v[204:207], v[22:25]
	v_mfma_f32_16x16x32_bf16 v[18:21], v[154:157], v[204:207], v[18:21]
	v_mfma_f32_16x16x32_bf16 v[6:9], v[146:149], v[220:223], v[6:9]
	v_mfma_f32_16x16x32_bf16 v[2:5], v[154:157], v[220:223], v[2:5]
	v_mfma_f32_16x16x32_bf16 v[54:57], v[150:153], v[178:181], v[54:57]
	v_mfma_f32_16x16x32_bf16 v[46:49], v[158:161], v[178:181], v[46:49]
	v_mfma_f32_16x16x32_bf16 v[38:41], v[150:153], v[200:203], v[38:41]
	v_mfma_f32_16x16x32_bf16 v[30:33], v[158:161], v[200:203], v[30:33]
	v_mfma_f32_16x16x32_bf16 v[22:25], v[150:153], v[216:219], v[22:25]
	v_mfma_f32_16x16x32_bf16 v[18:21], v[158:161], v[216:219], v[18:21]
	v_mfma_f32_16x16x32_bf16 v[6:9], v[150:153], v[224:227], v[6:9]
	v_mfma_f32_16x16x32_bf16 v[2:5], v[158:161], v[224:227], v[2:5]
	s_setprio 0
	s_barrier
	s_add_i32 s53, 0, 0x18000
	s_add_i32 s54, 0, 0x1c000
	v_add_u32_e32 v142, s53, v187
	v_add_u32_e32 v158, s54, v187
	ds_read_b128 v[130:133], v142
	ds_read_b128 v[134:137], v142 offset:1024
	ds_read_b128 v[138:141], v142 offset:2048
	ds_read_b128 v[142:145], v142 offset:3072
	ds_read_b128 v[146:149], v158
	ds_read_b128 v[150:153], v158 offset:1024
	ds_read_b128 v[154:157], v158 offset:2048
	ds_read_b128 v[158:161], v158 offset:3072
	s_add_u32 s36, s36, 0x80000
	s_addc_u32 s37, s37, 0
	s_mov_b32 m0, s45
	v_lshl_add_u64 v[212:213], s[36:37], 0, v[166:167]
	ds_read_b128 v[172:175], v199 offset:32768
	ds_read_b128 v[178:181], v199 offset:33792
	ds_read_b128 v[188:191], v199 offset:34816
	ds_read_b128 v[200:203], v199 offset:35840
	ds_read_b128 v[204:207], v199 offset:36864
	ds_read_b128 v[216:219], v199 offset:37888
	ds_read_b128 v[220:223], v199 offset:38912
	ds_read_b128 v[224:227], v199 offset:39936
	global_load_lds_dwordx4 v[212:213], off
	v_lshl_add_u64 v[212:213], s[36:37], 0, v[164:165]
	s_mov_b32 m0, s46
	s_nop 0
	global_load_lds_dwordx4 v[212:213], off
	s_waitcnt vmcnt(8) lgkmcnt(0)
	s_barrier
	s_setprio 1
	v_mfma_f32_16x16x32_bf16 v[126:129], v[130:133], v[172:175], v[126:129]
	v_mfma_f32_16x16x32_bf16 v[122:125], v[138:141], v[172:175], v[122:125]
	v_mfma_f32_16x16x32_bf16 v[110:113], v[130:133], v[188:191], v[110:113]
	v_mfma_f32_16x16x32_bf16 v[106:109], v[138:141], v[188:191], v[106:109]
	v_mfma_f32_16x16x32_bf16 v[98:101], v[130:133], v[204:207], v[98:101]
	v_mfma_f32_16x16x32_bf16 v[90:93], v[138:141], v[204:207], v[90:93]
	v_mfma_f32_16x16x32_bf16 v[82:85], v[130:133], v[220:223], v[82:85]
	v_mfma_f32_16x16x32_bf16 v[74:77], v[138:141], v[220:223], v[74:77]
	v_mfma_f32_16x16x32_bf16 v[126:129], v[134:137], v[178:181], v[126:129]
	v_mfma_f32_16x16x32_bf16 v[122:125], v[142:145], v[178:181], v[122:125]
	v_mfma_f32_16x16x32_bf16 v[110:113], v[134:137], v[200:203], v[110:113]
	v_mfma_f32_16x16x32_bf16 v[106:109], v[142:145], v[200:203], v[106:109]
	v_mfma_f32_16x16x32_bf16 v[98:101], v[134:137], v[216:219], v[98:101]
	v_mfma_f32_16x16x32_bf16 v[90:93], v[142:145], v[216:219], v[90:93]
	v_mfma_f32_16x16x32_bf16 v[82:85], v[134:137], v[224:227], v[82:85]
	v_mfma_f32_16x16x32_bf16 v[74:77], v[142:145], v[224:227], v[74:77]
	v_mfma_f32_16x16x32_bf16 v[118:121], v[146:149], v[172:175], v[118:121]
	v_mfma_f32_16x16x32_bf16 v[114:117], v[154:157], v[172:175], v[114:117]
	v_mfma_f32_16x16x32_bf16 v[102:105], v[146:149], v[188:191], v[102:105]
	v_mfma_f32_16x16x32_bf16 v[94:97], v[154:157], v[188:191], v[94:97]
	v_mfma_f32_16x16x32_bf16 v[86:89], v[146:149], v[204:207], v[86:89]
	v_mfma_f32_16x16x32_bf16 v[78:81], v[154:157], v[204:207], v[78:81]
	v_mfma_f32_16x16x32_bf16 v[70:73], v[146:149], v[220:223], v[70:73]
	v_mfma_f32_16x16x32_bf16 v[66:69], v[154:157], v[220:223], v[66:69]
	v_mfma_f32_16x16x32_bf16 v[118:121], v[150:153], v[178:181], v[118:121]
	v_mfma_f32_16x16x32_bf16 v[114:117], v[158:161], v[178:181], v[114:117]
	v_mfma_f32_16x16x32_bf16 v[102:105], v[150:153], v[200:203], v[102:105]
	v_mfma_f32_16x16x32_bf16 v[94:97], v[158:161], v[200:203], v[94:97]
	v_mfma_f32_16x16x32_bf16 v[86:89], v[150:153], v[216:219], v[86:89]
	v_mfma_f32_16x16x32_bf16 v[78:81], v[158:161], v[216:219], v[78:81]
	v_mfma_f32_16x16x32_bf16 v[70:73], v[150:153], v[224:227], v[70:73]
	v_mfma_f32_16x16x32_bf16 v[66:69], v[158:161], v[224:227], v[66:69]
	s_setprio 0
	s_barrier
	s_add_i32 s36, s53, s42
	v_lshl_add_u64 v[184:185], v[184:185], 0, s[64:65]
	s_mov_b32 m0, s36
	ds_read_b128 v[172:175], v199 offset:49152
	ds_read_b128 v[178:181], v199 offset:50176
	ds_read_b128 v[188:191], v199 offset:51200
	ds_read_b128 v[200:203], v199 offset:52224
	ds_read_b128 v[204:207], v199 offset:53248
	ds_read_b128 v[216:219], v199 offset:54272
	ds_read_b128 v[220:223], v199 offset:55296
	ds_read_b128 v[224:227], v199 offset:56320
	global_load_lds_dwordx4 v[184:185], off
	s_add_i32 m0, s36, 0x2000
	s_add_u32 s34, s34, 0x80080
	v_lshl_add_u64 v[184:185], v[192:193], 0, s[64:65]
	s_addc_u32 s35, s35, 0
	s_add_i32 s36, s54, s42
	global_load_lds_dwordx4 v[184:185], off
	v_lshl_add_u64 v[184:185], s[34:35], 0, v[210:211]
	s_mov_b32 m0, s36
	s_nop 0
	global_load_lds_dwordx4 v[184:185], off
	v_lshl_add_u64 v[184:185], s[34:35], 0, v[162:163]
	s_add_i32 m0, s36, 0x2000
	s_nop 0
	global_load_lds_dwordx4 v[184:185], off
	v_lshl_add_u64 v[184:185], v[196:197], 0, s[64:65]
	s_mov_b32 m0, s47
	s_nop 0
	global_load_lds_dwordx4 v[184:185], off
	v_lshl_add_u64 v[184:185], v[208:209], 0, s[64:65]
	s_mov_b32 m0, s48
	s_nop 0
	global_load_lds_dwordx4 v[184:185], off
	s_add_i32 s52, s52, 2
	s_add_u32 s6, s6, 0x100
	s_addc_u32 s7, s7, 0
	s_add_u32 s50, s50, 0x100
	s_addc_u32 s51, s51, 0
	s_cmp_gt_u32 s52, 29
	s_waitcnt vmcnt(8) lgkmcnt(0)
	s_barrier
	s_setprio 1
	v_mfma_f32_16x16x32_bf16 v[62:65], v[130:133], v[172:175], v[62:65]
	v_mfma_f32_16x16x32_bf16 v[58:61], v[138:141], v[172:175], v[58:61]
	v_mfma_f32_16x16x32_bf16 v[50:53], v[130:133], v[188:191], v[50:53]
	v_mfma_f32_16x16x32_bf16 v[42:45], v[138:141], v[188:191], v[42:45]
	v_mfma_f32_16x16x32_bf16 v[34:37], v[130:133], v[204:207], v[34:37]
	v_mfma_f32_16x16x32_bf16 v[26:29], v[138:141], v[204:207], v[26:29]
	v_mfma_f32_16x16x32_bf16 v[14:17], v[130:133], v[220:223], v[14:17]
	v_mfma_f32_16x16x32_bf16 v[10:13], v[138:141], v[220:223], v[10:13]
	v_mfma_f32_16x16x32_bf16 v[62:65], v[134:137], v[178:181], v[62:65]
	v_mfma_f32_16x16x32_bf16 v[58:61], v[142:145], v[178:181], v[58:61]
	v_mfma_f32_16x16x32_bf16 v[50:53], v[134:137], v[200:203], v[50:53]
	v_mfma_f32_16x16x32_bf16 v[42:45], v[142:145], v[200:203], v[42:45]
	v_mfma_f32_16x16x32_bf16 v[34:37], v[134:137], v[216:219], v[34:37]
	v_mfma_f32_16x16x32_bf16 v[26:29], v[142:145], v[216:219], v[26:29]
	v_mfma_f32_16x16x32_bf16 v[14:17], v[134:137], v[224:227], v[14:17]
	v_mfma_f32_16x16x32_bf16 v[10:13], v[142:145], v[224:227], v[10:13]
	v_mfma_f32_16x16x32_bf16 v[54:57], v[146:149], v[172:175], v[54:57]
	v_mfma_f32_16x16x32_bf16 v[46:49], v[154:157], v[172:175], v[46:49]
	v_mfma_f32_16x16x32_bf16 v[38:41], v[146:149], v[188:191], v[38:41]
	v_mfma_f32_16x16x32_bf16 v[30:33], v[154:157], v[188:191], v[30:33]
	v_mfma_f32_16x16x32_bf16 v[22:25], v[146:149], v[204:207], v[22:25]
	v_mfma_f32_16x16x32_bf16 v[18:21], v[154:157], v[204:207], v[18:21]
	v_mfma_f32_16x16x32_bf16 v[6:9], v[146:149], v[220:223], v[6:9]
	v_mfma_f32_16x16x32_bf16 v[2:5], v[154:157], v[220:223], v[2:5]
	v_mfma_f32_16x16x32_bf16 v[54:57], v[150:153], v[178:181], v[54:57]
	v_mfma_f32_16x16x32_bf16 v[46:49], v[158:161], v[178:181], v[46:49]
	v_mfma_f32_16x16x32_bf16 v[38:41], v[150:153], v[200:203], v[38:41]
	v_mfma_f32_16x16x32_bf16 v[30:33], v[158:161], v[200:203], v[30:33]
	v_mfma_f32_16x16x32_bf16 v[22:25], v[150:153], v[216:219], v[22:25]
	v_mfma_f32_16x16x32_bf16 v[18:21], v[158:161], v[216:219], v[18:21]
	v_mfma_f32_16x16x32_bf16 v[6:9], v[150:153], v[224:227], v[6:9]
	v_mfma_f32_16x16x32_bf16 v[2:5], v[158:161], v[224:227], v[2:5]
	s_setprio 0
	s_barrier
	s_cbranch_scc0 .LBB0_67
	s_and_b64 vcc, exec, s[18:19]
	s_cbranch_vccz .LBB0_70
	s_barrier

.LBB0_116:
	s_add_u32 s30, s6, 0xfff80080
	s_addc_u32 s31, s7, -1
	s_add_i32 s52, 0, 0x10000
	s_cmp_eq_u32 s51, 28
	s_cselect_b32 s35, s23, s31
	s_cselect_b32 s34, s28, s30
	s_cselect_b32 s31, s21, s50
	s_cselect_b32 s30, s29, s49
	s_add_i32 s54, 0, 0x14000
	v_add_u32_e32 v78, s52, v240
	v_add_u32_e32 v98, s54, v240
	ds_read_b128 v[66:69], v78
	ds_read_b128 v[70:73], v78 offset:1024
	ds_read_b128 v[74:77], v78 offset:2048
	ds_read_b128 v[78:81], v78 offset:3072
	ds_read_b128 v[82:85], v98
	ds_read_b128 v[86:89], v98 offset:1024
	ds_read_b128 v[90:93], v98 offset:2048
	ds_read_b128 v[98:101], v98 offset:3072
	v_lshl_add_u64 v[212:213], s[6:7], 0, v[182:183]
	s_add_i32 m0, s37, 0xc000
	ds_read_b128 v[186:189], v241
	ds_read_b128 v[190:193], v241 offset:1024
	ds_read_b128 v[194:197], v241 offset:2048
	ds_read_b128 v[198:201], v241 offset:3072
	ds_read_b128 v[202:205], v241 offset:4096
	ds_read_b128 v[206:209], v241 offset:5120
	ds_read_b128 v[216:219], v241 offset:6144
	ds_read_b128 v[220:223], v241 offset:7168
	global_load_lds_dwordx4 v[212:213], off
	v_lshl_add_u64 v[212:213], s[6:7], 0, v[184:185]
	s_add_i32 m0, s37, 0xe000
	s_nop 0
	global_load_lds_dwordx4 v[212:213], off
	s_waitcnt vmcnt(8) lgkmcnt(0)
	s_barrier
	s_setprio 1
	v_mfma_f32_16x16x32_bf16 v[158:161], v[66:69], v[186:189], v[158:161]
	v_mfma_f32_16x16x32_bf16 v[154:157], v[74:77], v[186:189], v[154:157]
	v_mfma_f32_16x16x32_bf16 v[142:145], v[66:69], v[194:197], v[142:145]
	v_mfma_f32_16x16x32_bf16 v[138:141], v[74:77], v[194:197], v[138:141]
	v_mfma_f32_16x16x32_bf16 v[126:129], v[66:69], v[202:205], v[126:129]
	v_mfma_f32_16x16x32_bf16 v[122:125], v[74:77], v[202:205], v[122:125]
	v_mfma_f32_16x16x32_bf16 v[110:113], v[66:69], v[216:219], v[110:113]
	v_mfma_f32_16x16x32_bf16 v[106:109], v[74:77], v[216:219], v[106:109]
	v_mfma_f32_16x16x32_bf16 v[158:161], v[70:73], v[190:193], v[158:161]
	v_mfma_f32_16x16x32_bf16 v[154:157], v[78:81], v[190:193], v[154:157]
	v_mfma_f32_16x16x32_bf16 v[142:145], v[70:73], v[198:201], v[142:145]
	v_mfma_f32_16x16x32_bf16 v[138:141], v[78:81], v[198:201], v[138:141]
	v_mfma_f32_16x16x32_bf16 v[126:129], v[70:73], v[206:209], v[126:129]
	v_mfma_f32_16x16x32_bf16 v[122:125], v[78:81], v[206:209], v[122:125]
	v_mfma_f32_16x16x32_bf16 v[110:113], v[70:73], v[220:223], v[110:113]
	v_mfma_f32_16x16x32_bf16 v[106:109], v[78:81], v[220:223], v[106:109]
	v_mfma_f32_16x16x32_bf16 v[150:153], v[82:85], v[186:189], v[150:153]
	v_mfma_f32_16x16x32_bf16 v[146:149], v[90:93], v[186:189], v[146:149]
	v_mfma_f32_16x16x32_bf16 v[134:137], v[82:85], v[194:197], v[134:137]
	v_mfma_f32_16x16x32_bf16 v[130:133], v[90:93], v[194:197], v[130:133]
	v_mfma_f32_16x16x32_bf16 v[118:121], v[82:85], v[202:205], v[118:121]
	v_mfma_f32_16x16x32_bf16 v[114:117], v[90:93], v[202:205], v[114:117]
	v_mfma_f32_16x16x32_bf16 v[102:105], v[82:85], v[216:219], v[102:105]
	v_mfma_f32_16x16x32_bf16 v[94:97], v[90:93], v[216:219], v[94:97]
	v_mfma_f32_16x16x32_bf16 v[150:153], v[86:89], v[190:193], v[150:153]
	v_mfma_f32_16x16x32_bf16 v[146:149], v[98:101], v[190:193], v[146:149]
	v_mfma_f32_16x16x32_bf16 v[134:137], v[86:89], v[198:201], v[134:137]
	v_mfma_f32_16x16x32_bf16 v[130:133], v[98:101], v[198:201], v[130:133]
	v_mfma_f32_16x16x32_bf16 v[118:121], v[86:89], v[206:209], v[118:121]
	v_mfma_f32_16x16x32_bf16 v[114:117], v[98:101], v[206:209], v[114:117]
	v_mfma_f32_16x16x32_bf16 v[102:105], v[86:89], v[220:223], v[102:105]
	v_mfma_f32_16x16x32_bf16 v[94:97], v[98:101], v[220:223], v[94:97]
	s_setprio 0
	s_barrier
	s_add_i32 s52, s52, s36
	v_lshl_add_u64 v[212:213], s[30:31], 0, v[166:167]
	s_mov_b32 m0, s52
	ds_read_b128 v[186:189], v241 offset:16384
	ds_read_b128 v[190:193], v241 offset:17408
	ds_read_b128 v[194:197], v241 offset:18432
	ds_read_b128 v[198:201], v241 offset:19456
	ds_read_b128 v[202:205], v241 offset:20480
	ds_read_b128 v[206:209], v241 offset:21504
	ds_read_b128 v[216:219], v241 offset:22528
	ds_read_b128 v[220:223], v241 offset:23552
	global_load_lds_dwordx4 v[212:213], off
	s_add_i32 m0, s52, 0x2000
	s_add_u32 s52, s30, 0x80000
	v_lshl_add_u64 v[214:215], s[30:31], 0, v[162:163]
	s_addc_u32 s53, s31, 0
	s_add_i32 s54, s54, s36
	global_load_lds_dwordx4 v[214:215], off
	v_lshl_add_u64 v[224:225], s[52:53], 0, v[166:167]
	s_mov_b32 m0, s54
	v_lshl_add_u64 v[226:227], s[34:35], 0, v[164:165]
	global_load_lds_dwordx4 v[224:225], off
	v_lshl_add_u64 v[224:225], s[52:53], 0, v[162:163]
	s_add_i32 m0, s54, 0x2000
	s_nop 0
	global_load_lds_dwordx4 v[224:225], off
	v_lshl_add_u64 v[224:225], s[34:35], 0, v[168:169]
	s_mov_b32 m0, s37
	s_nop 0
	global_load_lds_dwordx4 v[224:225], off
	s_mov_b32 m0, s42
	s_nop 0
	global_load_lds_dwordx4 v[226:227], off
	s_waitcnt vmcnt(8) lgkmcnt(0)
	s_barrier
	s_setprio 1
	v_mfma_f32_16x16x32_bf16 v[62:65], v[66:69], v[186:189], v[62:65]
	v_mfma_f32_16x16x32_bf16 v[58:61], v[74:77], v[186:189], v[58:61]
	v_mfma_f32_16x16x32_bf16 v[46:49], v[66:69], v[194:197], v[46:49]
	v_mfma_f32_16x16x32_bf16 v[42:45], v[74:77], v[194:197], v[42:45]
	v_mfma_f32_16x16x32_bf16 v[30:33], v[66:69], v[202:205], v[30:33]
	v_mfma_f32_16x16x32_bf16 v[26:29], v[74:77], v[202:205], v[26:29]
	v_mfma_f32_16x16x32_bf16 v[14:17], v[66:69], v[216:219], v[14:17]
	v_mfma_f32_16x16x32_bf16 v[10:13], v[74:77], v[216:219], v[10:13]
	v_mfma_f32_16x16x32_bf16 v[62:65], v[70:73], v[190:193], v[62:65]
	v_mfma_f32_16x16x32_bf16 v[58:61], v[78:81], v[190:193], v[58:61]
	v_mfma_f32_16x16x32_bf16 v[46:49], v[70:73], v[198:201], v[46:49]
	v_mfma_f32_16x16x32_bf16 v[42:45], v[78:81], v[198:201], v[42:45]
	v_mfma_f32_16x16x32_bf16 v[30:33], v[70:73], v[206:209], v[30:33]
	v_mfma_f32_16x16x32_bf16 v[26:29], v[78:81], v[206:209], v[26:29]
	v_mfma_f32_16x16x32_bf16 v[14:17], v[70:73], v[220:223], v[14:17]
	v_mfma_f32_16x16x32_bf16 v[10:13], v[78:81], v[220:223], v[10:13]
	v_mfma_f32_16x16x32_bf16 v[54:57], v[82:85], v[186:189], v[54:57]
	v_mfma_f32_16x16x32_bf16 v[50:53], v[90:93], v[186:189], v[50:53]
	v_mfma_f32_16x16x32_bf16 v[38:41], v[82:85], v[194:197], v[38:41]
	v_mfma_f32_16x16x32_bf16 v[34:37], v[90:93], v[194:197], v[34:37]
	v_mfma_f32_16x16x32_bf16 v[22:25], v[82:85], v[202:205], v[22:25]
	v_mfma_f32_16x16x32_bf16 v[18:21], v[90:93], v[202:205], v[18:21]
	v_mfma_f32_16x16x32_bf16 v[6:9], v[82:85], v[216:219], v[6:9]
	v_mfma_f32_16x16x32_bf16 v[2:5], v[90:93], v[216:219], v[2:5]
	v_mfma_f32_16x16x32_bf16 v[54:57], v[86:89], v[190:193], v[54:57]
	v_mfma_f32_16x16x32_bf16 v[50:53], v[98:101], v[190:193], v[50:53]
	v_mfma_f32_16x16x32_bf16 v[38:41], v[86:89], v[198:201], v[38:41]
	v_mfma_f32_16x16x32_bf16 v[34:37], v[98:101], v[198:201], v[34:37]
	v_mfma_f32_16x16x32_bf16 v[22:25], v[86:89], v[206:209], v[22:25]
	v_mfma_f32_16x16x32_bf16 v[18:21], v[98:101], v[206:209], v[18:21]
	v_mfma_f32_16x16x32_bf16 v[6:9], v[86:89], v[220:223], v[6:9]
	v_mfma_f32_16x16x32_bf16 v[2:5], v[98:101], v[220:223], v[2:5]
	s_setprio 0
	s_barrier
	s_add_i32 s52, 0, 0x18000
	s_add_i32 s53, 0, 0x1c000
	v_add_u32_e32 v78, s52, v240
	v_add_u32_e32 v98, s53, v240
	ds_read_b128 v[66:69], v78
	ds_read_b128 v[70:73], v78 offset:1024
	ds_read_b128 v[74:77], v78 offset:2048
	ds_read_b128 v[78:81], v78 offset:3072
	ds_read_b128 v[82:85], v98
	ds_read_b128 v[86:89], v98 offset:1024
	ds_read_b128 v[90:93], v98 offset:2048
	ds_read_b128 v[98:101], v98 offset:3072
	s_add_u32 s34, s34, 0x80000
	s_addc_u32 s35, s35, 0
	s_mov_b32 m0, s43
	v_lshl_add_u64 v[228:229], s[34:35], 0, v[168:169]
	ds_read_b128 v[186:189], v241 offset:32768
	ds_read_b128 v[190:193], v241 offset:33792
	ds_read_b128 v[194:197], v241 offset:34816
	ds_read_b128 v[198:201], v241 offset:35840
	ds_read_b128 v[202:205], v241 offset:36864
	ds_read_b128 v[206:209], v241 offset:37888
	ds_read_b128 v[216:219], v241 offset:38912
	ds_read_b128 v[220:223], v241 offset:39936
	global_load_lds_dwordx4 v[228:229], off
	v_lshl_add_u64 v[228:229], s[34:35], 0, v[164:165]
	s_mov_b32 m0, s44
	s_nop 0
	global_load_lds_dwordx4 v[228:229], off
	s_waitcnt vmcnt(8) lgkmcnt(0)
	s_barrier
	s_setprio 1
	v_mfma_f32_16x16x32_bf16 v[158:161], v[66:69], v[186:189], v[158:161]
	v_mfma_f32_16x16x32_bf16 v[154:157], v[74:77], v[186:189], v[154:157]
	v_mfma_f32_16x16x32_bf16 v[142:145], v[66:69], v[194:197], v[142:145]
	v_mfma_f32_16x16x32_bf16 v[138:141], v[74:77], v[194:197], v[138:141]
	v_mfma_f32_16x16x32_bf16 v[126:129], v[66:69], v[202:205], v[126:129]
	v_mfma_f32_16x16x32_bf16 v[122:125], v[74:77], v[202:205], v[122:125]
	v_mfma_f32_16x16x32_bf16 v[110:113], v[66:69], v[216:219], v[110:113]
	v_mfma_f32_16x16x32_bf16 v[106:109], v[74:77], v[216:219], v[106:109]
	v_mfma_f32_16x16x32_bf16 v[158:161], v[70:73], v[190:193], v[158:161]
	v_mfma_f32_16x16x32_bf16 v[154:157], v[78:81], v[190:193], v[154:157]
	v_mfma_f32_16x16x32_bf16 v[142:145], v[70:73], v[198:201], v[142:145]
	v_mfma_f32_16x16x32_bf16 v[138:141], v[78:81], v[198:201], v[138:141]
	v_mfma_f32_16x16x32_bf16 v[126:129], v[70:73], v[206:209], v[126:129]
	v_mfma_f32_16x16x32_bf16 v[122:125], v[78:81], v[206:209], v[122:125]
	v_mfma_f32_16x16x32_bf16 v[110:113], v[70:73], v[220:223], v[110:113]
	v_mfma_f32_16x16x32_bf16 v[106:109], v[78:81], v[220:223], v[106:109]
	v_mfma_f32_16x16x32_bf16 v[150:153], v[82:85], v[186:189], v[150:153]
	v_mfma_f32_16x16x32_bf16 v[146:149], v[90:93], v[186:189], v[146:149]
	v_mfma_f32_16x16x32_bf16 v[134:137], v[82:85], v[194:197], v[134:137]
	v_mfma_f32_16x16x32_bf16 v[130:133], v[90:93], v[194:197], v[130:133]
	v_mfma_f32_16x16x32_bf16 v[118:121], v[82:85], v[202:205], v[118:121]
	v_mfma_f32_16x16x32_bf16 v[114:117], v[90:93], v[202:205], v[114:117]
	v_mfma_f32_16x16x32_bf16 v[102:105], v[82:85], v[216:219], v[102:105]
	v_mfma_f32_16x16x32_bf16 v[94:97], v[90:93], v[216:219], v[94:97]
	v_mfma_f32_16x16x32_bf16 v[150:153], v[86:89], v[190:193], v[150:153]
	v_mfma_f32_16x16x32_bf16 v[146:149], v[98:101], v[190:193], v[146:149]
	v_mfma_f32_16x16x32_bf16 v[134:137], v[86:89], v[198:201], v[134:137]
	v_mfma_f32_16x16x32_bf16 v[130:133], v[98:101], v[198:201], v[130:133]
	v_mfma_f32_16x16x32_bf16 v[118:121], v[86:89], v[206:209], v[118:121]
	v_mfma_f32_16x16x32_bf16 v[114:117], v[98:101], v[206:209], v[114:117]
	v_mfma_f32_16x16x32_bf16 v[102:105], v[86:89], v[220:223], v[102:105]
	v_mfma_f32_16x16x32_bf16 v[94:97], v[98:101], v[220:223], v[94:97]
	s_setprio 0
	s_barrier
	s_add_i32 s34, s52, s36
	v_lshl_add_u64 v[212:213], v[212:213], 0, s[64:65]
	s_mov_b32 m0, s34
	ds_read_b128 v[186:189], v241 offset:49152
	ds_read_b128 v[190:193], v241 offset:50176
	ds_read_b128 v[194:197], v241 offset:51200
	ds_read_b128 v[198:201], v241 offset:52224
	ds_read_b128 v[202:205], v241 offset:53248
	ds_read_b128 v[206:209], v241 offset:54272
	ds_read_b128 v[216:219], v241 offset:55296
	ds_read_b128 v[220:223], v241 offset:56320
	global_load_lds_dwordx4 v[212:213], off
	s_add_i32 m0, s34, 0x2000
	s_add_u32 s30, s30, 0x80080
	v_lshl_add_u64 v[212:213], v[214:215], 0, s[64:65]
	s_addc_u32 s31, s31, 0
	s_add_i32 s34, s53, s36
	global_load_lds_dwordx4 v[212:213], off
	v_lshl_add_u64 v[212:213], s[30:31], 0, v[166:167]
	s_mov_b32 m0, s34
	s_nop 0
	global_load_lds_dwordx4 v[212:213], off
	v_lshl_add_u64 v[212:213], s[30:31], 0, v[162:163]
	s_add_i32 m0, s34, 0x2000
	s_nop 0
	global_load_lds_dwordx4 v[212:213], off
	v_lshl_add_u64 v[212:213], v[224:225], 0, s[64:65]
	s_mov_b32 m0, s46
	s_nop 0
	global_load_lds_dwordx4 v[212:213], off
	v_lshl_add_u64 v[212:213], v[226:227], 0, s[64:65]
	s_mov_b32 m0, s47
	s_nop 0
	global_load_lds_dwordx4 v[212:213], off
	s_add_i32 s51, s51, 2
	s_add_u32 s6, s6, 0x100
	s_addc_u32 s7, s7, 0
	s_add_u32 s49, s49, 0x100
	s_addc_u32 s50, s50, 0
	s_cmp_gt_u32 s51, 29
	s_waitcnt vmcnt(8) lgkmcnt(0)
	s_barrier
	s_setprio 1
	v_mfma_f32_16x16x32_bf16 v[62:65], v[66:69], v[186:189], v[62:65]
	v_mfma_f32_16x16x32_bf16 v[58:61], v[74:77], v[186:189], v[58:61]
	v_mfma_f32_16x16x32_bf16 v[46:49], v[66:69], v[194:197], v[46:49]
	v_mfma_f32_16x16x32_bf16 v[42:45], v[74:77], v[194:197], v[42:45]
	v_mfma_f32_16x16x32_bf16 v[30:33], v[66:69], v[202:205], v[30:33]
	v_mfma_f32_16x16x32_bf16 v[26:29], v[74:77], v[202:205], v[26:29]
	v_mfma_f32_16x16x32_bf16 v[14:17], v[66:69], v[216:219], v[14:17]
	v_mfma_f32_16x16x32_bf16 v[10:13], v[74:77], v[216:219], v[10:13]
	v_mfma_f32_16x16x32_bf16 v[62:65], v[70:73], v[190:193], v[62:65]
	v_mfma_f32_16x16x32_bf16 v[58:61], v[78:81], v[190:193], v[58:61]
	v_mfma_f32_16x16x32_bf16 v[46:49], v[70:73], v[198:201], v[46:49]
	v_mfma_f32_16x16x32_bf16 v[42:45], v[78:81], v[198:201], v[42:45]
	v_mfma_f32_16x16x32_bf16 v[30:33], v[70:73], v[206:209], v[30:33]
	v_mfma_f32_16x16x32_bf16 v[26:29], v[78:81], v[206:209], v[26:29]
	v_mfma_f32_16x16x32_bf16 v[14:17], v[70:73], v[220:223], v[14:17]
	v_mfma_f32_16x16x32_bf16 v[10:13], v[78:81], v[220:223], v[10:13]
	v_mfma_f32_16x16x32_bf16 v[54:57], v[82:85], v[186:189], v[54:57]
	v_mfma_f32_16x16x32_bf16 v[50:53], v[90:93], v[186:189], v[50:53]
	v_mfma_f32_16x16x32_bf16 v[38:41], v[82:85], v[194:197], v[38:41]
	v_mfma_f32_16x16x32_bf16 v[34:37], v[90:93], v[194:197], v[34:37]
	v_mfma_f32_16x16x32_bf16 v[22:25], v[82:85], v[202:205], v[22:25]
	v_mfma_f32_16x16x32_bf16 v[18:21], v[90:93], v[202:205], v[18:21]
	v_mfma_f32_16x16x32_bf16 v[6:9], v[82:85], v[216:219], v[6:9]
	v_mfma_f32_16x16x32_bf16 v[2:5], v[90:93], v[216:219], v[2:5]
	v_mfma_f32_16x16x32_bf16 v[54:57], v[86:89], v[190:193], v[54:57]
	v_mfma_f32_16x16x32_bf16 v[50:53], v[98:101], v[190:193], v[50:53]
	v_mfma_f32_16x16x32_bf16 v[38:41], v[86:89], v[198:201], v[38:41]
	v_mfma_f32_16x16x32_bf16 v[34:37], v[98:101], v[198:201], v[34:37]
	v_mfma_f32_16x16x32_bf16 v[22:25], v[86:89], v[206:209], v[22:25]
	v_mfma_f32_16x16x32_bf16 v[18:21], v[98:101], v[206:209], v[18:21]
	v_mfma_f32_16x16x32_bf16 v[6:9], v[86:89], v[220:223], v[6:9]
	v_mfma_f32_16x16x32_bf16 v[2:5], v[98:101], v[220:223], v[2:5]
	s_setprio 0
	s_barrier
	s_cbranch_scc0 .LBB0_116
	s_and_b64 vcc, exec, s[18:19]
	s_cbranch_vccz .LBB0_119
	s_barrier

.LBB0_226:
	s_add_u32 s30, s8, 0xfff80080
	s_addc_u32 s31, s9, -1
	s_add_i32 s54, 0, 0x10000
	s_cmp_eq_u32 s53, 28
	s_cselect_b32 s35, s23, s31
	s_cselect_b32 s34, s28, s30
	s_cselect_b32 s31, s21, s52
	s_cselect_b32 s30, s29, s51
	s_add_i32 s56, 0, 0x14000
	v_add_u32_e32 v160, s54, v141
	v_add_u32_e32 v176, s56, v141
	ds_read_b128 v[148:151], v160
	ds_read_b128 v[152:155], v160 offset:1024
	ds_read_b128 v[156:159], v160 offset:2048
	ds_read_b128 v[160:163], v160 offset:3072
	ds_read_b128 v[164:167], v176
	ds_read_b128 v[168:171], v176 offset:1024
	ds_read_b128 v[172:175], v176 offset:2048
	ds_read_b128 v[176:179], v176 offset:3072
	v_lshl_add_u64 v[208:209], s[8:9], 0, v[144:145]
	s_add_i32 m0, s41, 0xc000
	ds_read_b128 v[180:183], v238
	ds_read_b128 v[184:187], v238 offset:1024
	ds_read_b128 v[188:191], v238 offset:2048
	ds_read_b128 v[192:195], v238 offset:3072
	ds_read_b128 v[196:199], v238 offset:4096
	ds_read_b128 v[200:203], v238 offset:5120
	ds_read_b128 v[204:207], v238 offset:6144
	ds_read_b128 v[216:219], v238 offset:7168
	global_load_lds_dwordx4 v[208:209], off
	v_lshl_add_u64 v[208:209], s[8:9], 0, v[146:147]
	s_add_i32 m0, s41, 0xe000
	s_nop 0
	global_load_lds_dwordx4 v[208:209], off
	s_waitcnt vmcnt(8) lgkmcnt(0)
	s_barrier
	s_setprio 1
	v_mfma_f32_16x16x32_bf16 v[126:129], v[148:151], v[180:183], v[126:129]
	v_mfma_f32_16x16x32_bf16 v[122:125], v[156:159], v[180:183], v[122:125]
	v_mfma_f32_16x16x32_bf16 v[110:113], v[148:151], v[188:191], v[110:113]
	v_mfma_f32_16x16x32_bf16 v[106:109], v[156:159], v[188:191], v[106:109]
	v_mfma_f32_16x16x32_bf16 v[94:97], v[148:151], v[196:199], v[94:97]
	v_mfma_f32_16x16x32_bf16 v[90:93], v[156:159], v[196:199], v[90:93]
	v_mfma_f32_16x16x32_bf16 v[78:81], v[148:151], v[204:207], v[78:81]
	v_mfma_f32_16x16x32_bf16 v[74:77], v[156:159], v[204:207], v[74:77]
	v_mfma_f32_16x16x32_bf16 v[126:129], v[152:155], v[184:187], v[126:129]
	v_mfma_f32_16x16x32_bf16 v[122:125], v[160:163], v[184:187], v[122:125]
	v_mfma_f32_16x16x32_bf16 v[110:113], v[152:155], v[192:195], v[110:113]
	v_mfma_f32_16x16x32_bf16 v[106:109], v[160:163], v[192:195], v[106:109]
	v_mfma_f32_16x16x32_bf16 v[94:97], v[152:155], v[200:203], v[94:97]
	v_mfma_f32_16x16x32_bf16 v[90:93], v[160:163], v[200:203], v[90:93]
	v_mfma_f32_16x16x32_bf16 v[78:81], v[152:155], v[216:219], v[78:81]
	v_mfma_f32_16x16x32_bf16 v[74:77], v[160:163], v[216:219], v[74:77]
	v_mfma_f32_16x16x32_bf16 v[118:121], v[164:167], v[180:183], v[118:121]
	v_mfma_f32_16x16x32_bf16 v[114:117], v[172:175], v[180:183], v[114:117]
	v_mfma_f32_16x16x32_bf16 v[102:105], v[164:167], v[188:191], v[102:105]
	v_mfma_f32_16x16x32_bf16 v[98:101], v[172:175], v[188:191], v[98:101]
	v_mfma_f32_16x16x32_bf16 v[86:89], v[164:167], v[196:199], v[86:89]
	v_mfma_f32_16x16x32_bf16 v[82:85], v[172:175], v[196:199], v[82:85]
	v_mfma_f32_16x16x32_bf16 v[70:73], v[164:167], v[204:207], v[70:73]
	v_mfma_f32_16x16x32_bf16 v[66:69], v[172:175], v[204:207], v[66:69]
	v_mfma_f32_16x16x32_bf16 v[118:121], v[168:171], v[184:187], v[118:121]
	v_mfma_f32_16x16x32_bf16 v[114:117], v[176:179], v[184:187], v[114:117]
	v_mfma_f32_16x16x32_bf16 v[102:105], v[168:171], v[192:195], v[102:105]
	v_mfma_f32_16x16x32_bf16 v[98:101], v[176:179], v[192:195], v[98:101]
	v_mfma_f32_16x16x32_bf16 v[86:89], v[168:171], v[200:203], v[86:89]
	v_mfma_f32_16x16x32_bf16 v[82:85], v[176:179], v[200:203], v[82:85]
	v_mfma_f32_16x16x32_bf16 v[70:73], v[168:171], v[216:219], v[70:73]
	v_mfma_f32_16x16x32_bf16 v[66:69], v[176:179], v[216:219], v[66:69]
	s_setprio 0
	s_barrier
	s_add_i32 s54, s54, s40
	v_lshl_add_u64 v[208:209], s[30:31], 0, v[134:135]
	s_mov_b32 m0, s54
	ds_read_b128 v[180:183], v238 offset:16384
	ds_read_b128 v[184:187], v238 offset:17408
	ds_read_b128 v[188:191], v238 offset:18432
	ds_read_b128 v[192:195], v238 offset:19456
	ds_read_b128 v[196:199], v238 offset:20480
	ds_read_b128 v[200:203], v238 offset:21504
	ds_read_b128 v[204:207], v238 offset:22528
	ds_read_b128 v[216:219], v238 offset:23552
	global_load_lds_dwordx4 v[208:209], off
	s_add_i32 m0, s54, 0x2000
	s_add_u32 s54, s30, 0x80000
	v_lshl_add_u64 v[212:213], s[30:31], 0, v[130:131]
	s_addc_u32 s55, s31, 0
	s_add_i32 s56, s56, s40
	global_load_lds_dwordx4 v[212:213], off
	v_lshl_add_u64 v[214:215], s[54:55], 0, v[134:135]
	s_mov_b32 m0, s56
	v_lshl_add_u64 v[220:221], s[34:35], 0, v[132:133]
	global_load_lds_dwordx4 v[214:215], off
	v_lshl_add_u64 v[214:215], s[54:55], 0, v[130:131]
	s_add_i32 m0, s56, 0x2000
	s_nop 0
	global_load_lds_dwordx4 v[214:215], off
	v_lshl_add_u64 v[214:215], s[34:35], 0, v[136:137]
	s_mov_b32 m0, s41
	s_nop 0
	global_load_lds_dwordx4 v[214:215], off
	s_mov_b32 m0, s42
	s_nop 0
	global_load_lds_dwordx4 v[220:221], off
	s_waitcnt vmcnt(8) lgkmcnt(0)
	s_barrier
	s_setprio 1
	v_mfma_f32_16x16x32_bf16 v[62:65], v[148:151], v[180:183], v[62:65]
	v_mfma_f32_16x16x32_bf16 v[58:61], v[156:159], v[180:183], v[58:61]
	v_mfma_f32_16x16x32_bf16 v[46:49], v[148:151], v[188:191], v[46:49]
	v_mfma_f32_16x16x32_bf16 v[42:45], v[156:159], v[188:191], v[42:45]
	v_mfma_f32_16x16x32_bf16 v[30:33], v[148:151], v[196:199], v[30:33]
	v_mfma_f32_16x16x32_bf16 v[26:29], v[156:159], v[196:199], v[26:29]
	v_mfma_f32_16x16x32_bf16 v[14:17], v[148:151], v[204:207], v[14:17]
	v_mfma_f32_16x16x32_bf16 v[10:13], v[156:159], v[204:207], v[10:13]
	v_mfma_f32_16x16x32_bf16 v[62:65], v[152:155], v[184:187], v[62:65]
	v_mfma_f32_16x16x32_bf16 v[58:61], v[160:163], v[184:187], v[58:61]
	v_mfma_f32_16x16x32_bf16 v[46:49], v[152:155], v[192:195], v[46:49]
	v_mfma_f32_16x16x32_bf16 v[42:45], v[160:163], v[192:195], v[42:45]
	v_mfma_f32_16x16x32_bf16 v[30:33], v[152:155], v[200:203], v[30:33]
	v_mfma_f32_16x16x32_bf16 v[26:29], v[160:163], v[200:203], v[26:29]
	v_mfma_f32_16x16x32_bf16 v[14:17], v[152:155], v[216:219], v[14:17]
	v_mfma_f32_16x16x32_bf16 v[10:13], v[160:163], v[216:219], v[10:13]
	v_mfma_f32_16x16x32_bf16 v[54:57], v[164:167], v[180:183], v[54:57]
	v_mfma_f32_16x16x32_bf16 v[50:53], v[172:175], v[180:183], v[50:53]
	v_mfma_f32_16x16x32_bf16 v[38:41], v[164:167], v[188:191], v[38:41]
	v_mfma_f32_16x16x32_bf16 v[34:37], v[172:175], v[188:191], v[34:37]
	v_mfma_f32_16x16x32_bf16 v[22:25], v[164:167], v[196:199], v[22:25]
	v_mfma_f32_16x16x32_bf16 v[18:21], v[172:175], v[196:199], v[18:21]
	v_mfma_f32_16x16x32_bf16 v[6:9], v[164:167], v[204:207], v[6:9]
	v_mfma_f32_16x16x32_bf16 v[2:5], v[172:175], v[204:207], v[2:5]
	v_mfma_f32_16x16x32_bf16 v[54:57], v[168:171], v[184:187], v[54:57]
	v_mfma_f32_16x16x32_bf16 v[50:53], v[176:179], v[184:187], v[50:53]
	v_mfma_f32_16x16x32_bf16 v[38:41], v[168:171], v[192:195], v[38:41]
	v_mfma_f32_16x16x32_bf16 v[34:37], v[176:179], v[192:195], v[34:37]
	v_mfma_f32_16x16x32_bf16 v[22:25], v[168:171], v[200:203], v[22:25]
	v_mfma_f32_16x16x32_bf16 v[18:21], v[176:179], v[200:203], v[18:21]
	v_mfma_f32_16x16x32_bf16 v[6:9], v[168:171], v[216:219], v[6:9]
	v_mfma_f32_16x16x32_bf16 v[2:5], v[176:179], v[216:219], v[2:5]
	s_setprio 0
	s_barrier
	s_add_i32 s54, 0, 0x18000
	s_add_i32 s55, 0, 0x1c000
	v_add_u32_e32 v160, s54, v141
	v_add_u32_e32 v176, s55, v141
	ds_read_b128 v[148:151], v160
	ds_read_b128 v[152:155], v160 offset:1024
	ds_read_b128 v[156:159], v160 offset:2048
	ds_read_b128 v[160:163], v160 offset:3072
	ds_read_b128 v[164:167], v176
	ds_read_b128 v[168:171], v176 offset:1024
	ds_read_b128 v[172:175], v176 offset:2048
	ds_read_b128 v[176:179], v176 offset:3072
	s_add_u32 s34, s34, 0x80000
	s_addc_u32 s35, s35, 0
	s_mov_b32 m0, s43
	v_lshl_add_u64 v[222:223], s[34:35], 0, v[136:137]
	ds_read_b128 v[180:183], v238 offset:32768
	ds_read_b128 v[184:187], v238 offset:33792
	ds_read_b128 v[188:191], v238 offset:34816
	ds_read_b128 v[192:195], v238 offset:35840
	ds_read_b128 v[196:199], v238 offset:36864
	ds_read_b128 v[200:203], v238 offset:37888
	ds_read_b128 v[204:207], v238 offset:38912
	ds_read_b128 v[216:219], v238 offset:39936
	global_load_lds_dwordx4 v[222:223], off
	v_lshl_add_u64 v[222:223], s[34:35], 0, v[132:133]
	s_mov_b32 m0, s44
	s_nop 0
	global_load_lds_dwordx4 v[222:223], off
	s_waitcnt vmcnt(8) lgkmcnt(0)
	s_barrier
	s_setprio 1
	v_mfma_f32_16x16x32_bf16 v[126:129], v[148:151], v[180:183], v[126:129]
	v_mfma_f32_16x16x32_bf16 v[122:125], v[156:159], v[180:183], v[122:125]
	v_mfma_f32_16x16x32_bf16 v[110:113], v[148:151], v[188:191], v[110:113]
	v_mfma_f32_16x16x32_bf16 v[106:109], v[156:159], v[188:191], v[106:109]
	v_mfma_f32_16x16x32_bf16 v[94:97], v[148:151], v[196:199], v[94:97]
	v_mfma_f32_16x16x32_bf16 v[90:93], v[156:159], v[196:199], v[90:93]
	v_mfma_f32_16x16x32_bf16 v[78:81], v[148:151], v[204:207], v[78:81]
	v_mfma_f32_16x16x32_bf16 v[74:77], v[156:159], v[204:207], v[74:77]
	v_mfma_f32_16x16x32_bf16 v[126:129], v[152:155], v[184:187], v[126:129]
	v_mfma_f32_16x16x32_bf16 v[122:125], v[160:163], v[184:187], v[122:125]
	v_mfma_f32_16x16x32_bf16 v[110:113], v[152:155], v[192:195], v[110:113]
	v_mfma_f32_16x16x32_bf16 v[106:109], v[160:163], v[192:195], v[106:109]
	v_mfma_f32_16x16x32_bf16 v[94:97], v[152:155], v[200:203], v[94:97]
	v_mfma_f32_16x16x32_bf16 v[90:93], v[160:163], v[200:203], v[90:93]
	v_mfma_f32_16x16x32_bf16 v[78:81], v[152:155], v[216:219], v[78:81]
	v_mfma_f32_16x16x32_bf16 v[74:77], v[160:163], v[216:219], v[74:77]
	v_mfma_f32_16x16x32_bf16 v[118:121], v[164:167], v[180:183], v[118:121]
	v_mfma_f32_16x16x32_bf16 v[114:117], v[172:175], v[180:183], v[114:117]
	v_mfma_f32_16x16x32_bf16 v[102:105], v[164:167], v[188:191], v[102:105]
	v_mfma_f32_16x16x32_bf16 v[98:101], v[172:175], v[188:191], v[98:101]
	v_mfma_f32_16x16x32_bf16 v[86:89], v[164:167], v[196:199], v[86:89]
	v_mfma_f32_16x16x32_bf16 v[82:85], v[172:175], v[196:199], v[82:85]
	v_mfma_f32_16x16x32_bf16 v[70:73], v[164:167], v[204:207], v[70:73]
	v_mfma_f32_16x16x32_bf16 v[66:69], v[172:175], v[204:207], v[66:69]
	v_mfma_f32_16x16x32_bf16 v[118:121], v[168:171], v[184:187], v[118:121]
	v_mfma_f32_16x16x32_bf16 v[114:117], v[176:179], v[184:187], v[114:117]
	v_mfma_f32_16x16x32_bf16 v[102:105], v[168:171], v[192:195], v[102:105]
	v_mfma_f32_16x16x32_bf16 v[98:101], v[176:179], v[192:195], v[98:101]
	v_mfma_f32_16x16x32_bf16 v[86:89], v[168:171], v[200:203], v[86:89]
	v_mfma_f32_16x16x32_bf16 v[82:85], v[176:179], v[200:203], v[82:85]
	v_mfma_f32_16x16x32_bf16 v[70:73], v[168:171], v[216:219], v[70:73]
	v_mfma_f32_16x16x32_bf16 v[66:69], v[176:179], v[216:219], v[66:69]
	s_setprio 0
	s_barrier
	s_add_i32 s34, s54, s40
	v_lshl_add_u64 v[208:209], v[208:209], 0, s[64:65]
	s_mov_b32 m0, s34
	ds_read_b128 v[180:183], v238 offset:49152
	ds_read_b128 v[184:187], v238 offset:50176
	ds_read_b128 v[188:191], v238 offset:51200
	ds_read_b128 v[192:195], v238 offset:52224
	ds_read_b128 v[196:199], v238 offset:53248
	ds_read_b128 v[200:203], v238 offset:54272
	ds_read_b128 v[204:207], v238 offset:55296
	ds_read_b128 v[216:219], v238 offset:56320
	global_load_lds_dwordx4 v[208:209], off
	s_add_i32 m0, s34, 0x2000
	s_add_u32 s30, s30, 0x80080
	v_lshl_add_u64 v[208:209], v[212:213], 0, s[64:65]
	s_addc_u32 s31, s31, 0
	s_add_i32 s34, s55, s40
	global_load_lds_dwordx4 v[208:209], off
	v_lshl_add_u64 v[208:209], s[30:31], 0, v[134:135]
	s_mov_b32 m0, s34
	s_nop 0
	global_load_lds_dwordx4 v[208:209], off
	v_lshl_add_u64 v[208:209], s[30:31], 0, v[130:131]
	s_add_i32 m0, s34, 0x2000
	s_nop 0
	global_load_lds_dwordx4 v[208:209], off
	v_lshl_add_u64 v[208:209], v[214:215], 0, s[64:65]
	s_mov_b32 m0, s46
	s_nop 0
	global_load_lds_dwordx4 v[208:209], off
	v_lshl_add_u64 v[208:209], v[220:221], 0, s[64:65]
	s_mov_b32 m0, s47
	s_nop 0
	global_load_lds_dwordx4 v[208:209], off
	s_add_i32 s53, s53, 2
	s_add_u32 s8, s8, 0x100
	s_addc_u32 s9, s9, 0
	s_add_u32 s51, s51, 0x100
	s_addc_u32 s52, s52, 0
	s_cmp_gt_u32 s53, 29
	s_waitcnt vmcnt(8) lgkmcnt(0)
	s_barrier
	s_setprio 1
	v_mfma_f32_16x16x32_bf16 v[62:65], v[148:151], v[180:183], v[62:65]
	v_mfma_f32_16x16x32_bf16 v[58:61], v[156:159], v[180:183], v[58:61]
	v_mfma_f32_16x16x32_bf16 v[46:49], v[148:151], v[188:191], v[46:49]
	v_mfma_f32_16x16x32_bf16 v[42:45], v[156:159], v[188:191], v[42:45]
	v_mfma_f32_16x16x32_bf16 v[30:33], v[148:151], v[196:199], v[30:33]
	v_mfma_f32_16x16x32_bf16 v[26:29], v[156:159], v[196:199], v[26:29]
	v_mfma_f32_16x16x32_bf16 v[14:17], v[148:151], v[204:207], v[14:17]
	v_mfma_f32_16x16x32_bf16 v[10:13], v[156:159], v[204:207], v[10:13]
	v_mfma_f32_16x16x32_bf16 v[62:65], v[152:155], v[184:187], v[62:65]
	v_mfma_f32_16x16x32_bf16 v[58:61], v[160:163], v[184:187], v[58:61]
	v_mfma_f32_16x16x32_bf16 v[46:49], v[152:155], v[192:195], v[46:49]
	v_mfma_f32_16x16x32_bf16 v[42:45], v[160:163], v[192:195], v[42:45]
	v_mfma_f32_16x16x32_bf16 v[30:33], v[152:155], v[200:203], v[30:33]
	v_mfma_f32_16x16x32_bf16 v[26:29], v[160:163], v[200:203], v[26:29]
	v_mfma_f32_16x16x32_bf16 v[14:17], v[152:155], v[216:219], v[14:17]
	v_mfma_f32_16x16x32_bf16 v[10:13], v[160:163], v[216:219], v[10:13]
	v_mfma_f32_16x16x32_bf16 v[54:57], v[164:167], v[180:183], v[54:57]
	v_mfma_f32_16x16x32_bf16 v[50:53], v[172:175], v[180:183], v[50:53]
	v_mfma_f32_16x16x32_bf16 v[38:41], v[164:167], v[188:191], v[38:41]
	v_mfma_f32_16x16x32_bf16 v[34:37], v[172:175], v[188:191], v[34:37]
	v_mfma_f32_16x16x32_bf16 v[22:25], v[164:167], v[196:199], v[22:25]
	v_mfma_f32_16x16x32_bf16 v[18:21], v[172:175], v[196:199], v[18:21]
	v_mfma_f32_16x16x32_bf16 v[6:9], v[164:167], v[204:207], v[6:9]
	v_mfma_f32_16x16x32_bf16 v[2:5], v[172:175], v[204:207], v[2:5]
	v_mfma_f32_16x16x32_bf16 v[54:57], v[168:171], v[184:187], v[54:57]
	v_mfma_f32_16x16x32_bf16 v[50:53], v[176:179], v[184:187], v[50:53]
	v_mfma_f32_16x16x32_bf16 v[38:41], v[168:171], v[192:195], v[38:41]
	v_mfma_f32_16x16x32_bf16 v[34:37], v[176:179], v[192:195], v[34:37]
	v_mfma_f32_16x16x32_bf16 v[22:25], v[168:171], v[200:203], v[22:25]
	v_mfma_f32_16x16x32_bf16 v[18:21], v[176:179], v[200:203], v[18:21]
	v_mfma_f32_16x16x32_bf16 v[6:9], v[168:171], v[216:219], v[6:9]
	v_mfma_f32_16x16x32_bf16 v[2:5], v[176:179], v[216:219], v[2:5]
	s_setprio 0
	s_barrier
	s_cbranch_scc0 .LBB0_226
	s_and_b64 vcc, exec, s[18:19]
	s_cbranch_vccz .LBB0_229
	s_barrier

.LBB0_956:
	s_add_u32 s10, s34, 0x100
	s_addc_u32 s11, s35, 0
	s_add_i32 s63, 0, 0x10000
	s_cmp_eq_u32 s62, 28
	s_cselect_b32 s47, s2, s11
	s_cselect_b32 s46, s3, s10
	s_cselect_b32 s43, s31, s61
	s_cselect_b32 s42, s37, s60
	s_add_i32 s66, 0, 0x14000
	v_add_u32_e32 v78, s63, v251
	v_add_u32_e32 v94, s66, v251
	ds_read_b128 v[66:69], v78
	ds_read_b128 v[70:73], v78 offset:1024
	ds_read_b128 v[74:77], v78 offset:2048
	ds_read_b128 v[78:81], v78 offset:3072
	ds_read_b128 v[82:85], v94
	ds_read_b128 v[86:89], v94 offset:1024
	ds_read_b128 v[90:93], v94 offset:2048
	ds_read_b128 v[94:97], v94 offset:3072
	v_lshl_add_u64 v[194:195], s[34:35], 0, v[218:219]
	s_add_i32 m0, s51, 0xc000
	ds_read_b128 v[162:165], v244
	ds_read_b128 v[166:169], v244 offset:1024
	ds_read_b128 v[170:173], v244 offset:2048
	ds_read_b128 v[174:177], v244 offset:3072
	ds_read_b128 v[178:181], v244 offset:4096
	ds_read_b128 v[182:185], v244 offset:5120
	ds_read_b128 v[186:189], v244 offset:6144
	ds_read_b128 v[190:193], v244 offset:7168
	global_load_lds_dwordx4 v[194:195], off
	v_lshl_add_u64 v[194:195], s[34:35], 0, v[220:221]
	s_add_i32 m0, s51, 0xe000
	s_nop 0
	global_load_lds_dwordx4 v[194:195], off
	s_waitcnt vmcnt(8) lgkmcnt(0)
	s_barrier
	s_setprio 1
	v_mfma_f32_16x16x32_bf16 v[158:161], v[66:69], v[162:165], v[158:161]
	v_mfma_f32_16x16x32_bf16 v[154:157], v[74:77], v[162:165], v[154:157]
	v_mfma_f32_16x16x32_bf16 v[142:145], v[66:69], v[170:173], v[142:145]
	v_mfma_f32_16x16x32_bf16 v[138:141], v[74:77], v[170:173], v[138:141]
	v_mfma_f32_16x16x32_bf16 v[126:129], v[66:69], v[178:181], v[126:129]
	v_mfma_f32_16x16x32_bf16 v[122:125], v[74:77], v[178:181], v[122:125]
	v_mfma_f32_16x16x32_bf16 v[110:113], v[66:69], v[186:189], v[110:113]
	v_mfma_f32_16x16x32_bf16 v[106:109], v[74:77], v[186:189], v[106:109]
	v_mfma_f32_16x16x32_bf16 v[158:161], v[70:73], v[166:169], v[158:161]
	v_mfma_f32_16x16x32_bf16 v[154:157], v[78:81], v[166:169], v[154:157]
	v_mfma_f32_16x16x32_bf16 v[142:145], v[70:73], v[174:177], v[142:145]
	v_mfma_f32_16x16x32_bf16 v[138:141], v[78:81], v[174:177], v[138:141]
	v_mfma_f32_16x16x32_bf16 v[126:129], v[70:73], v[182:185], v[126:129]
	v_mfma_f32_16x16x32_bf16 v[122:125], v[78:81], v[182:185], v[122:125]
	v_mfma_f32_16x16x32_bf16 v[110:113], v[70:73], v[190:193], v[110:113]
	v_mfma_f32_16x16x32_bf16 v[106:109], v[78:81], v[190:193], v[106:109]
	v_mfma_f32_16x16x32_bf16 v[150:153], v[82:85], v[162:165], v[150:153]
	v_mfma_f32_16x16x32_bf16 v[146:149], v[90:93], v[162:165], v[146:149]
	v_mfma_f32_16x16x32_bf16 v[134:137], v[82:85], v[170:173], v[134:137]
	v_mfma_f32_16x16x32_bf16 v[130:133], v[90:93], v[170:173], v[130:133]
	v_mfma_f32_16x16x32_bf16 v[118:121], v[82:85], v[178:181], v[118:121]
	v_mfma_f32_16x16x32_bf16 v[114:117], v[90:93], v[178:181], v[114:117]
	v_mfma_f32_16x16x32_bf16 v[102:105], v[82:85], v[186:189], v[102:105]
	v_mfma_f32_16x16x32_bf16 v[98:101], v[90:93], v[186:189], v[98:101]
	v_mfma_f32_16x16x32_bf16 v[150:153], v[86:89], v[166:169], v[150:153]
	v_mfma_f32_16x16x32_bf16 v[146:149], v[94:97], v[166:169], v[146:149]
	v_mfma_f32_16x16x32_bf16 v[134:137], v[86:89], v[174:177], v[134:137]
	v_mfma_f32_16x16x32_bf16 v[130:133], v[94:97], v[174:177], v[130:133]
	v_mfma_f32_16x16x32_bf16 v[118:121], v[86:89], v[182:185], v[118:121]
	v_mfma_f32_16x16x32_bf16 v[114:117], v[94:97], v[182:185], v[114:117]
	v_mfma_f32_16x16x32_bf16 v[102:105], v[86:89], v[190:193], v[102:105]
	v_mfma_f32_16x16x32_bf16 v[98:101], v[94:97], v[190:193], v[98:101]
	s_setprio 0
	s_barrier
	s_add_i32 s34, s63, s44
	v_lshl_add_u64 v[194:195], s[42:43], 0, v[210:211]
	s_mov_b32 m0, s34
	ds_read_b128 v[162:165], v244 offset:16384
	ds_read_b128 v[166:169], v244 offset:17408
	ds_read_b128 v[170:173], v244 offset:18432
	ds_read_b128 v[174:177], v244 offset:19456
	ds_read_b128 v[178:181], v244 offset:20480
	ds_read_b128 v[182:185], v244 offset:21504
	ds_read_b128 v[186:189], v244 offset:22528
	ds_read_b128 v[190:193], v244 offset:23552
	global_load_lds_dwordx4 v[194:195], off
	s_add_i32 m0, s34, 0x2000
	s_add_u32 s34, s42, 0x80000
	v_lshl_add_u64 v[196:197], s[42:43], 0, v[216:217]
	s_addc_u32 s35, s43, 0
	s_add_i32 s63, s66, s44
	global_load_lds_dwordx4 v[196:197], off
	v_lshl_add_u64 v[198:199], s[34:35], 0, v[210:211]
	s_mov_b32 m0, s63
	v_lshl_add_u64 v[200:201], s[46:47], 0, v[216:217]
	global_load_lds_dwordx4 v[198:199], off
	v_lshl_add_u64 v[198:199], s[34:35], 0, v[216:217]
	s_add_i32 m0, s63, 0x2000
	s_nop 0
	global_load_lds_dwordx4 v[198:199], off
	v_lshl_add_u64 v[198:199], s[46:47], 0, v[210:211]
	s_mov_b32 m0, s51
	s_nop 0
	global_load_lds_dwordx4 v[198:199], off
	s_mov_b32 m0, s52
	s_nop 0
	global_load_lds_dwordx4 v[200:201], off
	s_waitcnt vmcnt(8) lgkmcnt(0)
	s_barrier
	s_setprio 1
	v_mfma_f32_16x16x32_bf16 v[62:65], v[66:69], v[162:165], v[62:65]
	v_mfma_f32_16x16x32_bf16 v[58:61], v[74:77], v[162:165], v[58:61]
	v_mfma_f32_16x16x32_bf16 v[46:49], v[66:69], v[170:173], v[46:49]
	v_mfma_f32_16x16x32_bf16 v[42:45], v[74:77], v[170:173], v[42:45]
	v_mfma_f32_16x16x32_bf16 v[30:33], v[66:69], v[178:181], v[30:33]
	v_mfma_f32_16x16x32_bf16 v[26:29], v[74:77], v[178:181], v[26:29]
	v_mfma_f32_16x16x32_bf16 v[14:17], v[66:69], v[186:189], v[14:17]
	v_mfma_f32_16x16x32_bf16 v[10:13], v[74:77], v[186:189], v[10:13]
	v_mfma_f32_16x16x32_bf16 v[62:65], v[70:73], v[166:169], v[62:65]
	v_mfma_f32_16x16x32_bf16 v[58:61], v[78:81], v[166:169], v[58:61]
	v_mfma_f32_16x16x32_bf16 v[46:49], v[70:73], v[174:177], v[46:49]
	v_mfma_f32_16x16x32_bf16 v[42:45], v[78:81], v[174:177], v[42:45]
	v_mfma_f32_16x16x32_bf16 v[30:33], v[70:73], v[182:185], v[30:33]
	v_mfma_f32_16x16x32_bf16 v[26:29], v[78:81], v[182:185], v[26:29]
	v_mfma_f32_16x16x32_bf16 v[14:17], v[70:73], v[190:193], v[14:17]
	v_mfma_f32_16x16x32_bf16 v[10:13], v[78:81], v[190:193], v[10:13]
	v_mfma_f32_16x16x32_bf16 v[54:57], v[82:85], v[162:165], v[54:57]
	v_mfma_f32_16x16x32_bf16 v[50:53], v[90:93], v[162:165], v[50:53]
	v_mfma_f32_16x16x32_bf16 v[38:41], v[82:85], v[170:173], v[38:41]
	v_mfma_f32_16x16x32_bf16 v[34:37], v[90:93], v[170:173], v[34:37]
	v_mfma_f32_16x16x32_bf16 v[22:25], v[82:85], v[178:181], v[22:25]
	v_mfma_f32_16x16x32_bf16 v[18:21], v[90:93], v[178:181], v[18:21]
	v_mfma_f32_16x16x32_bf16 v[6:9], v[82:85], v[186:189], v[6:9]
	v_mfma_f32_16x16x32_bf16 v[2:5], v[90:93], v[186:189], v[2:5]
	v_mfma_f32_16x16x32_bf16 v[54:57], v[86:89], v[166:169], v[54:57]
	v_mfma_f32_16x16x32_bf16 v[50:53], v[94:97], v[166:169], v[50:53]
	v_mfma_f32_16x16x32_bf16 v[38:41], v[86:89], v[174:177], v[38:41]
	v_mfma_f32_16x16x32_bf16 v[34:37], v[94:97], v[174:177], v[34:37]
	v_mfma_f32_16x16x32_bf16 v[22:25], v[86:89], v[182:185], v[22:25]
	v_mfma_f32_16x16x32_bf16 v[18:21], v[94:97], v[182:185], v[18:21]
	v_mfma_f32_16x16x32_bf16 v[6:9], v[86:89], v[190:193], v[6:9]
	v_mfma_f32_16x16x32_bf16 v[2:5], v[94:97], v[190:193], v[2:5]
	s_setprio 0
	s_barrier
	s_add_i32 s63, 0, 0x18000
	s_add_i32 s66, 0, 0x1c000
	v_add_u32_e32 v78, s63, v251
	v_add_u32_e32 v94, s66, v251
	ds_read_b128 v[66:69], v78
	ds_read_b128 v[70:73], v78 offset:1024
	ds_read_b128 v[74:77], v78 offset:2048
	ds_read_b128 v[78:81], v78 offset:3072
	ds_read_b128 v[82:85], v94
	ds_read_b128 v[86:89], v94 offset:1024
	ds_read_b128 v[90:93], v94 offset:2048
	ds_read_b128 v[94:97], v94 offset:3072
	s_add_u32 s34, s46, 0x80000
	s_addc_u32 s35, s47, 0
	s_mov_b32 m0, s53
	v_lshl_add_u64 v[202:203], s[34:35], 0, v[210:211]
	ds_read_b128 v[162:165], v244 offset:32768
	ds_read_b128 v[166:169], v244 offset:33792
	ds_read_b128 v[170:173], v244 offset:34816
	ds_read_b128 v[174:177], v244 offset:35840
	ds_read_b128 v[178:181], v244 offset:36864
	ds_read_b128 v[182:185], v244 offset:37888
	ds_read_b128 v[186:189], v244 offset:38912
	ds_read_b128 v[190:193], v244 offset:39936
	global_load_lds_dwordx4 v[202:203], off
	v_lshl_add_u64 v[202:203], s[34:35], 0, v[216:217]
	s_mov_b32 m0, s54
	s_nop 0
	global_load_lds_dwordx4 v[202:203], off
	s_waitcnt vmcnt(8) lgkmcnt(0)
	s_barrier
	s_setprio 1
	v_mfma_f32_16x16x32_bf16 v[158:161], v[66:69], v[162:165], v[158:161]
	v_mfma_f32_16x16x32_bf16 v[154:157], v[74:77], v[162:165], v[154:157]
	v_mfma_f32_16x16x32_bf16 v[142:145], v[66:69], v[170:173], v[142:145]
	v_mfma_f32_16x16x32_bf16 v[138:141], v[74:77], v[170:173], v[138:141]
	v_mfma_f32_16x16x32_bf16 v[126:129], v[66:69], v[178:181], v[126:129]
	v_mfma_f32_16x16x32_bf16 v[122:125], v[74:77], v[178:181], v[122:125]
	v_mfma_f32_16x16x32_bf16 v[110:113], v[66:69], v[186:189], v[110:113]
	v_mfma_f32_16x16x32_bf16 v[106:109], v[74:77], v[186:189], v[106:109]
	v_mfma_f32_16x16x32_bf16 v[158:161], v[70:73], v[166:169], v[158:161]
	v_mfma_f32_16x16x32_bf16 v[154:157], v[78:81], v[166:169], v[154:157]
	v_mfma_f32_16x16x32_bf16 v[142:145], v[70:73], v[174:177], v[142:145]
	v_mfma_f32_16x16x32_bf16 v[138:141], v[78:81], v[174:177], v[138:141]
	v_mfma_f32_16x16x32_bf16 v[126:129], v[70:73], v[182:185], v[126:129]
	v_mfma_f32_16x16x32_bf16 v[122:125], v[78:81], v[182:185], v[122:125]
	v_mfma_f32_16x16x32_bf16 v[110:113], v[70:73], v[190:193], v[110:113]
	v_mfma_f32_16x16x32_bf16 v[106:109], v[78:81], v[190:193], v[106:109]
	v_mfma_f32_16x16x32_bf16 v[150:153], v[82:85], v[162:165], v[150:153]
	v_mfma_f32_16x16x32_bf16 v[146:149], v[90:93], v[162:165], v[146:149]
	v_mfma_f32_16x16x32_bf16 v[134:137], v[82:85], v[170:173], v[134:137]
	v_mfma_f32_16x16x32_bf16 v[130:133], v[90:93], v[170:173], v[130:133]
	v_mfma_f32_16x16x32_bf16 v[118:121], v[82:85], v[178:181], v[118:121]
	v_mfma_f32_16x16x32_bf16 v[114:117], v[90:93], v[178:181], v[114:117]
	v_mfma_f32_16x16x32_bf16 v[102:105], v[82:85], v[186:189], v[102:105]
	v_mfma_f32_16x16x32_bf16 v[98:101], v[90:93], v[186:189], v[98:101]
	v_mfma_f32_16x16x32_bf16 v[150:153], v[86:89], v[166:169], v[150:153]
	v_mfma_f32_16x16x32_bf16 v[146:149], v[94:97], v[166:169], v[146:149]
	v_mfma_f32_16x16x32_bf16 v[134:137], v[86:89], v[174:177], v[134:137]
	v_mfma_f32_16x16x32_bf16 v[130:133], v[94:97], v[174:177], v[130:133]
	v_mfma_f32_16x16x32_bf16 v[118:121], v[86:89], v[182:185], v[118:121]
	v_mfma_f32_16x16x32_bf16 v[114:117], v[94:97], v[182:185], v[114:117]
	v_mfma_f32_16x16x32_bf16 v[102:105], v[86:89], v[190:193], v[102:105]
	v_mfma_f32_16x16x32_bf16 v[98:101], v[94:97], v[190:193], v[98:101]
	s_setprio 0
	s_barrier
	s_add_i32 s34, s63, s44
	v_lshl_add_u64 v[194:195], v[194:195], 0, s[64:65]
	s_mov_b32 m0, s34
	ds_read_b128 v[162:165], v244 offset:49152
	ds_read_b128 v[166:169], v244 offset:50176
	ds_read_b128 v[170:173], v244 offset:51200
	ds_read_b128 v[174:177], v244 offset:52224
	ds_read_b128 v[178:181], v244 offset:53248
	ds_read_b128 v[182:185], v244 offset:54272
	ds_read_b128 v[186:189], v244 offset:55296
	ds_read_b128 v[190:193], v244 offset:56320
	global_load_lds_dwordx4 v[194:195], off
	s_add_i32 m0, s34, 0x2000
	s_add_u32 s34, s42, 0x80080
	v_lshl_add_u64 v[194:195], v[196:197], 0, s[64:65]
	s_addc_u32 s35, s43, 0
	s_add_i32 s42, s66, s44
	global_load_lds_dwordx4 v[194:195], off
	v_lshl_add_u64 v[194:195], s[34:35], 0, v[210:211]
	s_mov_b32 m0, s42
	s_nop 0
	global_load_lds_dwordx4 v[194:195], off
	v_lshl_add_u64 v[194:195], s[34:35], 0, v[216:217]
	s_add_i32 m0, s42, 0x2000
	s_nop 0
	global_load_lds_dwordx4 v[194:195], off
	v_lshl_add_u64 v[194:195], v[198:199], 0, s[64:65]
	s_mov_b32 m0, s55
	s_nop 0
	global_load_lds_dwordx4 v[194:195], off
	v_lshl_add_u64 v[194:195], v[200:201], 0, s[64:65]
	s_mov_b32 m0, s56
	s_nop 0
	global_load_lds_dwordx4 v[194:195], off
	s_add_i32 s62, s62, 2
	s_add_u32 s60, s60, 0x100
	s_addc_u32 s61, s61, 0
	s_cmp_gt_u32 s62, 29
	s_mov_b64 s[34:35], s[10:11]
	s_waitcnt vmcnt(8) lgkmcnt(0)
	s_barrier
	s_setprio 1
	v_mfma_f32_16x16x32_bf16 v[62:65], v[66:69], v[162:165], v[62:65]
	v_mfma_f32_16x16x32_bf16 v[58:61], v[74:77], v[162:165], v[58:61]
	v_mfma_f32_16x16x32_bf16 v[46:49], v[66:69], v[170:173], v[46:49]
	v_mfma_f32_16x16x32_bf16 v[42:45], v[74:77], v[170:173], v[42:45]
	v_mfma_f32_16x16x32_bf16 v[30:33], v[66:69], v[178:181], v[30:33]
	v_mfma_f32_16x16x32_bf16 v[26:29], v[74:77], v[178:181], v[26:29]
	v_mfma_f32_16x16x32_bf16 v[14:17], v[66:69], v[186:189], v[14:17]
	v_mfma_f32_16x16x32_bf16 v[10:13], v[74:77], v[186:189], v[10:13]
	v_mfma_f32_16x16x32_bf16 v[62:65], v[70:73], v[166:169], v[62:65]
	v_mfma_f32_16x16x32_bf16 v[58:61], v[78:81], v[166:169], v[58:61]
	v_mfma_f32_16x16x32_bf16 v[46:49], v[70:73], v[174:177], v[46:49]
	v_mfma_f32_16x16x32_bf16 v[42:45], v[78:81], v[174:177], v[42:45]
	v_mfma_f32_16x16x32_bf16 v[30:33], v[70:73], v[182:185], v[30:33]
	v_mfma_f32_16x16x32_bf16 v[26:29], v[78:81], v[182:185], v[26:29]
	v_mfma_f32_16x16x32_bf16 v[14:17], v[70:73], v[190:193], v[14:17]
	v_mfma_f32_16x16x32_bf16 v[10:13], v[78:81], v[190:193], v[10:13]
	v_mfma_f32_16x16x32_bf16 v[54:57], v[82:85], v[162:165], v[54:57]
	v_mfma_f32_16x16x32_bf16 v[50:53], v[90:93], v[162:165], v[50:53]
	v_mfma_f32_16x16x32_bf16 v[38:41], v[82:85], v[170:173], v[38:41]
	v_mfma_f32_16x16x32_bf16 v[34:37], v[90:93], v[170:173], v[34:37]
	v_mfma_f32_16x16x32_bf16 v[22:25], v[82:85], v[178:181], v[22:25]
	v_mfma_f32_16x16x32_bf16 v[18:21], v[90:93], v[178:181], v[18:21]
	v_mfma_f32_16x16x32_bf16 v[6:9], v[82:85], v[186:189], v[6:9]
	v_mfma_f32_16x16x32_bf16 v[2:5], v[90:93], v[186:189], v[2:5]
	v_mfma_f32_16x16x32_bf16 v[54:57], v[86:89], v[166:169], v[54:57]
	v_mfma_f32_16x16x32_bf16 v[50:53], v[94:97], v[166:169], v[50:53]
	v_mfma_f32_16x16x32_bf16 v[38:41], v[86:89], v[174:177], v[38:41]
	v_mfma_f32_16x16x32_bf16 v[34:37], v[94:97], v[174:177], v[34:37]
	v_mfma_f32_16x16x32_bf16 v[22:25], v[86:89], v[182:185], v[22:25]
	v_mfma_f32_16x16x32_bf16 v[18:21], v[94:97], v[182:185], v[18:21]
	v_mfma_f32_16x16x32_bf16 v[6:9], v[86:89], v[190:193], v[6:9]
	v_mfma_f32_16x16x32_bf16 v[2:5], v[94:97], v[190:193], v[2:5]
	s_setprio 0
	s_barrier
	s_cbranch_scc0 .LBB0_956
	s_and_b64 vcc, exec, s[26:27]
	s_cbranch_vccz .LBB0_959
	s_barrier

.LBB0_1091:
	s_add_u32 s30, s26, 0xfff80080
	s_addc_u32 s31, s27, -1
	s_add_i32 s51, 0, 0x10000
	s_cmp_eq_u32 s50, 28
	s_cselect_b32 s35, s2, s31
	s_cselect_b32 s34, s3, s30
	s_cselect_b32 s31, s19, s49
	s_cselect_b32 s30, s21, s48
	s_add_i32 s54, 0, 0x14000
	v_add_u32_e32 v142, s51, v181
	v_add_u32_e32 v158, s54, v181
	ds_read_b128 v[130:133], v142
	ds_read_b128 v[134:137], v142 offset:1024
	ds_read_b128 v[138:141], v142 offset:2048
	ds_read_b128 v[142:145], v142 offset:3072
	ds_read_b128 v[146:149], v158
	ds_read_b128 v[150:153], v158 offset:1024
	ds_read_b128 v[154:157], v158 offset:2048
	ds_read_b128 v[158:161], v158 offset:3072
	v_lshl_add_u64 v[172:173], s[26:27], 0, v[168:169]
	s_add_i32 m0, s41, 0xc000
	ds_read_b128 v[176:179], v195
	ds_read_b128 v[182:185], v195 offset:1024
	ds_read_b128 v[190:193], v195 offset:2048
	ds_read_b128 v[196:199], v195 offset:3072
	ds_read_b128 v[200:203], v195 offset:4096
	ds_read_b128 v[204:207], v195 offset:5120
	ds_read_b128 v[216:219], v195 offset:6144
	ds_read_b128 v[220:223], v195 offset:7168
	global_load_lds_dwordx4 v[172:173], off
	v_lshl_add_u64 v[172:173], s[26:27], 0, v[170:171]
	s_add_i32 m0, s41, 0xe000
	s_nop 0
	global_load_lds_dwordx4 v[172:173], off
	s_waitcnt vmcnt(8) lgkmcnt(0)
	s_barrier
	s_setprio 1
	v_mfma_f32_16x16x32_bf16 v[126:129], v[130:133], v[176:179], v[126:129]
	v_mfma_f32_16x16x32_bf16 v[122:125], v[138:141], v[176:179], v[122:125]
	v_mfma_f32_16x16x32_bf16 v[110:113], v[130:133], v[190:193], v[110:113]
	v_mfma_f32_16x16x32_bf16 v[106:109], v[138:141], v[190:193], v[106:109]
	v_mfma_f32_16x16x32_bf16 v[94:97], v[130:133], v[200:203], v[94:97]
	v_mfma_f32_16x16x32_bf16 v[90:93], v[138:141], v[200:203], v[90:93]
	v_mfma_f32_16x16x32_bf16 v[78:81], v[130:133], v[216:219], v[78:81]
	v_mfma_f32_16x16x32_bf16 v[74:77], v[138:141], v[216:219], v[74:77]
	v_mfma_f32_16x16x32_bf16 v[126:129], v[134:137], v[182:185], v[126:129]
	v_mfma_f32_16x16x32_bf16 v[122:125], v[142:145], v[182:185], v[122:125]
	v_mfma_f32_16x16x32_bf16 v[110:113], v[134:137], v[196:199], v[110:113]
	v_mfma_f32_16x16x32_bf16 v[106:109], v[142:145], v[196:199], v[106:109]
	v_mfma_f32_16x16x32_bf16 v[94:97], v[134:137], v[204:207], v[94:97]
	v_mfma_f32_16x16x32_bf16 v[90:93], v[142:145], v[204:207], v[90:93]
	v_mfma_f32_16x16x32_bf16 v[78:81], v[134:137], v[220:223], v[78:81]
	v_mfma_f32_16x16x32_bf16 v[74:77], v[142:145], v[220:223], v[74:77]
	v_mfma_f32_16x16x32_bf16 v[118:121], v[146:149], v[176:179], v[118:121]
	v_mfma_f32_16x16x32_bf16 v[114:117], v[154:157], v[176:179], v[114:117]
	v_mfma_f32_16x16x32_bf16 v[102:105], v[146:149], v[190:193], v[102:105]
	v_mfma_f32_16x16x32_bf16 v[98:101], v[154:157], v[190:193], v[98:101]
	v_mfma_f32_16x16x32_bf16 v[86:89], v[146:149], v[200:203], v[86:89]
	v_mfma_f32_16x16x32_bf16 v[82:85], v[154:157], v[200:203], v[82:85]
	v_mfma_f32_16x16x32_bf16 v[70:73], v[146:149], v[216:219], v[70:73]
	v_mfma_f32_16x16x32_bf16 v[66:69], v[154:157], v[216:219], v[66:69]
	v_mfma_f32_16x16x32_bf16 v[118:121], v[150:153], v[182:185], v[118:121]
	v_mfma_f32_16x16x32_bf16 v[114:117], v[158:161], v[182:185], v[114:117]
	v_mfma_f32_16x16x32_bf16 v[102:105], v[150:153], v[196:199], v[102:105]
	v_mfma_f32_16x16x32_bf16 v[98:101], v[158:161], v[196:199], v[98:101]
	v_mfma_f32_16x16x32_bf16 v[86:89], v[150:153], v[204:207], v[86:89]
	v_mfma_f32_16x16x32_bf16 v[82:85], v[158:161], v[204:207], v[82:85]
	v_mfma_f32_16x16x32_bf16 v[70:73], v[150:153], v[220:223], v[70:73]
	v_mfma_f32_16x16x32_bf16 v[66:69], v[158:161], v[220:223], v[66:69]
	s_setprio 0
	s_barrier
	s_add_i32 s51, s51, s40
	v_lshl_add_u64 v[172:173], s[30:31], 0, v[210:211]
	s_mov_b32 m0, s51
	ds_read_b128 v[176:179], v195 offset:16384
	ds_read_b128 v[182:185], v195 offset:17408
	ds_read_b128 v[190:193], v195 offset:18432
	ds_read_b128 v[196:199], v195 offset:19456
	ds_read_b128 v[200:203], v195 offset:20480
	ds_read_b128 v[204:207], v195 offset:21504
	ds_read_b128 v[216:219], v195 offset:22528
	ds_read_b128 v[220:223], v195 offset:23552
	global_load_lds_dwordx4 v[172:173], off
	s_add_i32 m0, s51, 0x2000
	s_add_u32 s52, s30, 0x80000
	v_lshl_add_u64 v[186:187], s[30:31], 0, v[162:163]
	s_addc_u32 s53, s31, 0
	s_add_i32 s51, s54, s40
	global_load_lds_dwordx4 v[186:187], off
	v_lshl_add_u64 v[208:209], s[52:53], 0, v[210:211]
	s_mov_b32 m0, s51
	v_lshl_add_u64 v[212:213], s[34:35], 0, v[164:165]
	global_load_lds_dwordx4 v[208:209], off
	v_lshl_add_u64 v[208:209], s[52:53], 0, v[162:163]
	s_add_i32 m0, s51, 0x2000
	s_nop 0
	global_load_lds_dwordx4 v[208:209], off
	v_lshl_add_u64 v[208:209], s[34:35], 0, v[166:167]
	s_mov_b32 m0, s41
	s_nop 0
	global_load_lds_dwordx4 v[208:209], off
	s_mov_b32 m0, s42
	s_nop 0
	global_load_lds_dwordx4 v[212:213], off
	s_waitcnt vmcnt(8) lgkmcnt(0)
	s_barrier
	s_setprio 1
	v_mfma_f32_16x16x32_bf16 v[62:65], v[130:133], v[176:179], v[62:65]
	v_mfma_f32_16x16x32_bf16 v[58:61], v[138:141], v[176:179], v[58:61]
	v_mfma_f32_16x16x32_bf16 v[46:49], v[130:133], v[190:193], v[46:49]
	v_mfma_f32_16x16x32_bf16 v[42:45], v[138:141], v[190:193], v[42:45]
	v_mfma_f32_16x16x32_bf16 v[30:33], v[130:133], v[200:203], v[30:33]
	v_mfma_f32_16x16x32_bf16 v[26:29], v[138:141], v[200:203], v[26:29]
	v_mfma_f32_16x16x32_bf16 v[14:17], v[130:133], v[216:219], v[14:17]
	v_mfma_f32_16x16x32_bf16 v[10:13], v[138:141], v[216:219], v[10:13]
	v_mfma_f32_16x16x32_bf16 v[62:65], v[134:137], v[182:185], v[62:65]
	v_mfma_f32_16x16x32_bf16 v[58:61], v[142:145], v[182:185], v[58:61]
	v_mfma_f32_16x16x32_bf16 v[46:49], v[134:137], v[196:199], v[46:49]
	v_mfma_f32_16x16x32_bf16 v[42:45], v[142:145], v[196:199], v[42:45]
	v_mfma_f32_16x16x32_bf16 v[30:33], v[134:137], v[204:207], v[30:33]
	v_mfma_f32_16x16x32_bf16 v[26:29], v[142:145], v[204:207], v[26:29]
	v_mfma_f32_16x16x32_bf16 v[14:17], v[134:137], v[220:223], v[14:17]
	v_mfma_f32_16x16x32_bf16 v[10:13], v[142:145], v[220:223], v[10:13]
	v_mfma_f32_16x16x32_bf16 v[54:57], v[146:149], v[176:179], v[54:57]
	v_mfma_f32_16x16x32_bf16 v[50:53], v[154:157], v[176:179], v[50:53]
	v_mfma_f32_16x16x32_bf16 v[38:41], v[146:149], v[190:193], v[38:41]
	v_mfma_f32_16x16x32_bf16 v[34:37], v[154:157], v[190:193], v[34:37]
	v_mfma_f32_16x16x32_bf16 v[22:25], v[146:149], v[200:203], v[22:25]
	v_mfma_f32_16x16x32_bf16 v[18:21], v[154:157], v[200:203], v[18:21]
	v_mfma_f32_16x16x32_bf16 v[6:9], v[146:149], v[216:219], v[6:9]
	v_mfma_f32_16x16x32_bf16 v[2:5], v[154:157], v[216:219], v[2:5]
	v_mfma_f32_16x16x32_bf16 v[54:57], v[150:153], v[182:185], v[54:57]
	v_mfma_f32_16x16x32_bf16 v[50:53], v[158:161], v[182:185], v[50:53]
	v_mfma_f32_16x16x32_bf16 v[38:41], v[150:153], v[196:199], v[38:41]
	v_mfma_f32_16x16x32_bf16 v[34:37], v[158:161], v[196:199], v[34:37]
	v_mfma_f32_16x16x32_bf16 v[22:25], v[150:153], v[204:207], v[22:25]
	v_mfma_f32_16x16x32_bf16 v[18:21], v[158:161], v[204:207], v[18:21]
	v_mfma_f32_16x16x32_bf16 v[6:9], v[150:153], v[220:223], v[6:9]
	v_mfma_f32_16x16x32_bf16 v[2:5], v[158:161], v[220:223], v[2:5]
	s_setprio 0
	s_barrier
	s_add_i32 s51, 0, 0x18000
	s_add_i32 s52, 0, 0x1c000
	v_add_u32_e32 v142, s51, v181
	v_add_u32_e32 v158, s52, v181
	ds_read_b128 v[130:133], v142
	ds_read_b128 v[134:137], v142 offset:1024
	ds_read_b128 v[138:141], v142 offset:2048
	ds_read_b128 v[142:145], v142 offset:3072
	ds_read_b128 v[146:149], v158
	ds_read_b128 v[150:153], v158 offset:1024
	ds_read_b128 v[154:157], v158 offset:2048
	ds_read_b128 v[158:161], v158 offset:3072
	s_add_u32 s34, s34, 0x80000
	s_addc_u32 s35, s35, 0
	s_mov_b32 m0, s43
	v_lshl_add_u64 v[214:215], s[34:35], 0, v[166:167]
	ds_read_b128 v[176:179], v195 offset:32768
	ds_read_b128 v[182:185], v195 offset:33792
	ds_read_b128 v[190:193], v195 offset:34816
	ds_read_b128 v[196:199], v195 offset:35840
	ds_read_b128 v[200:203], v195 offset:36864
	ds_read_b128 v[204:207], v195 offset:37888
	ds_read_b128 v[216:219], v195 offset:38912
	ds_read_b128 v[220:223], v195 offset:39936
	global_load_lds_dwordx4 v[214:215], off
	v_lshl_add_u64 v[214:215], s[34:35], 0, v[164:165]
	s_mov_b32 m0, s44
	s_nop 0
	global_load_lds_dwordx4 v[214:215], off
	s_waitcnt vmcnt(8) lgkmcnt(0)
	s_barrier
	s_setprio 1
	v_mfma_f32_16x16x32_bf16 v[126:129], v[130:133], v[176:179], v[126:129]
	v_mfma_f32_16x16x32_bf16 v[122:125], v[138:141], v[176:179], v[122:125]
	v_mfma_f32_16x16x32_bf16 v[110:113], v[130:133], v[190:193], v[110:113]
	v_mfma_f32_16x16x32_bf16 v[106:109], v[138:141], v[190:193], v[106:109]
	v_mfma_f32_16x16x32_bf16 v[94:97], v[130:133], v[200:203], v[94:97]
	v_mfma_f32_16x16x32_bf16 v[90:93], v[138:141], v[200:203], v[90:93]
	v_mfma_f32_16x16x32_bf16 v[78:81], v[130:133], v[216:219], v[78:81]
	v_mfma_f32_16x16x32_bf16 v[74:77], v[138:141], v[216:219], v[74:77]
	v_mfma_f32_16x16x32_bf16 v[126:129], v[134:137], v[182:185], v[126:129]
	v_mfma_f32_16x16x32_bf16 v[122:125], v[142:145], v[182:185], v[122:125]
	v_mfma_f32_16x16x32_bf16 v[110:113], v[134:137], v[196:199], v[110:113]
	v_mfma_f32_16x16x32_bf16 v[106:109], v[142:145], v[196:199], v[106:109]
	v_mfma_f32_16x16x32_bf16 v[94:97], v[134:137], v[204:207], v[94:97]
	v_mfma_f32_16x16x32_bf16 v[90:93], v[142:145], v[204:207], v[90:93]
	v_mfma_f32_16x16x32_bf16 v[78:81], v[134:137], v[220:223], v[78:81]
	v_mfma_f32_16x16x32_bf16 v[74:77], v[142:145], v[220:223], v[74:77]
	v_mfma_f32_16x16x32_bf16 v[118:121], v[146:149], v[176:179], v[118:121]
	v_mfma_f32_16x16x32_bf16 v[114:117], v[154:157], v[176:179], v[114:117]
	v_mfma_f32_16x16x32_bf16 v[102:105], v[146:149], v[190:193], v[102:105]
	v_mfma_f32_16x16x32_bf16 v[98:101], v[154:157], v[190:193], v[98:101]
	v_mfma_f32_16x16x32_bf16 v[86:89], v[146:149], v[200:203], v[86:89]
	v_mfma_f32_16x16x32_bf16 v[82:85], v[154:157], v[200:203], v[82:85]
	v_mfma_f32_16x16x32_bf16 v[70:73], v[146:149], v[216:219], v[70:73]
	v_mfma_f32_16x16x32_bf16 v[66:69], v[154:157], v[216:219], v[66:69]
	v_mfma_f32_16x16x32_bf16 v[118:121], v[150:153], v[182:185], v[118:121]
	v_mfma_f32_16x16x32_bf16 v[114:117], v[158:161], v[182:185], v[114:117]
	v_mfma_f32_16x16x32_bf16 v[102:105], v[150:153], v[196:199], v[102:105]
	v_mfma_f32_16x16x32_bf16 v[98:101], v[158:161], v[196:199], v[98:101]
	v_mfma_f32_16x16x32_bf16 v[86:89], v[150:153], v[204:207], v[86:89]
	v_mfma_f32_16x16x32_bf16 v[82:85], v[158:161], v[204:207], v[82:85]
	v_mfma_f32_16x16x32_bf16 v[70:73], v[150:153], v[220:223], v[70:73]
	v_mfma_f32_16x16x32_bf16 v[66:69], v[158:161], v[220:223], v[66:69]
	s_setprio 0
	s_barrier
	s_add_i32 s34, s51, s40
	v_lshl_add_u64 v[172:173], v[172:173], 0, s[64:65]
	s_mov_b32 m0, s34
	ds_read_b128 v[176:179], v195 offset:49152
	ds_read_b128 v[182:185], v195 offset:50176
	ds_read_b128 v[190:193], v195 offset:51200
	ds_read_b128 v[196:199], v195 offset:52224
	ds_read_b128 v[200:203], v195 offset:53248
	ds_read_b128 v[204:207], v195 offset:54272
	ds_read_b128 v[216:219], v195 offset:55296
	ds_read_b128 v[220:223], v195 offset:56320
	global_load_lds_dwordx4 v[172:173], off
	s_add_i32 m0, s34, 0x2000
	s_add_u32 s30, s30, 0x80080
	v_lshl_add_u64 v[172:173], v[186:187], 0, s[64:65]
	s_addc_u32 s31, s31, 0
	s_add_i32 s34, s52, s40
	global_load_lds_dwordx4 v[172:173], off
	v_lshl_add_u64 v[172:173], s[30:31], 0, v[210:211]
	s_mov_b32 m0, s34
	s_nop 0
	global_load_lds_dwordx4 v[172:173], off
	v_lshl_add_u64 v[172:173], s[30:31], 0, v[162:163]
	s_add_i32 m0, s34, 0x2000
	s_nop 0
	global_load_lds_dwordx4 v[172:173], off
	v_lshl_add_u64 v[172:173], v[208:209], 0, s[64:65]
	s_mov_b32 m0, s45
	s_nop 0
	global_load_lds_dwordx4 v[172:173], off
	v_lshl_add_u64 v[172:173], v[212:213], 0, s[64:65]
	s_mov_b32 m0, s46
	s_nop 0
	global_load_lds_dwordx4 v[172:173], off
	s_add_i32 s50, s50, 2
	s_add_u32 s26, s26, 0x100
	s_addc_u32 s27, s27, 0
	s_add_u32 s48, s48, 0x100
	s_addc_u32 s49, s49, 0
	s_cmp_gt_u32 s50, 29
	s_waitcnt vmcnt(8) lgkmcnt(0)
	s_barrier
	s_setprio 1
	v_mfma_f32_16x16x32_bf16 v[62:65], v[130:133], v[176:179], v[62:65]
	v_mfma_f32_16x16x32_bf16 v[58:61], v[138:141], v[176:179], v[58:61]
	v_mfma_f32_16x16x32_bf16 v[46:49], v[130:133], v[190:193], v[46:49]
	v_mfma_f32_16x16x32_bf16 v[42:45], v[138:141], v[190:193], v[42:45]
	v_mfma_f32_16x16x32_bf16 v[30:33], v[130:133], v[200:203], v[30:33]
	v_mfma_f32_16x16x32_bf16 v[26:29], v[138:141], v[200:203], v[26:29]
	v_mfma_f32_16x16x32_bf16 v[14:17], v[130:133], v[216:219], v[14:17]
	v_mfma_f32_16x16x32_bf16 v[10:13], v[138:141], v[216:219], v[10:13]
	v_mfma_f32_16x16x32_bf16 v[62:65], v[134:137], v[182:185], v[62:65]
	v_mfma_f32_16x16x32_bf16 v[58:61], v[142:145], v[182:185], v[58:61]
	v_mfma_f32_16x16x32_bf16 v[46:49], v[134:137], v[196:199], v[46:49]
	v_mfma_f32_16x16x32_bf16 v[42:45], v[142:145], v[196:199], v[42:45]
	v_mfma_f32_16x16x32_bf16 v[30:33], v[134:137], v[204:207], v[30:33]
	v_mfma_f32_16x16x32_bf16 v[26:29], v[142:145], v[204:207], v[26:29]
	v_mfma_f32_16x16x32_bf16 v[14:17], v[134:137], v[220:223], v[14:17]
	v_mfma_f32_16x16x32_bf16 v[10:13], v[142:145], v[220:223], v[10:13]
	v_mfma_f32_16x16x32_bf16 v[54:57], v[146:149], v[176:179], v[54:57]
	v_mfma_f32_16x16x32_bf16 v[50:53], v[154:157], v[176:179], v[50:53]
	v_mfma_f32_16x16x32_bf16 v[38:41], v[146:149], v[190:193], v[38:41]
	v_mfma_f32_16x16x32_bf16 v[34:37], v[154:157], v[190:193], v[34:37]
	v_mfma_f32_16x16x32_bf16 v[22:25], v[146:149], v[200:203], v[22:25]
	v_mfma_f32_16x16x32_bf16 v[18:21], v[154:157], v[200:203], v[18:21]
	v_mfma_f32_16x16x32_bf16 v[6:9], v[146:149], v[216:219], v[6:9]
	v_mfma_f32_16x16x32_bf16 v[2:5], v[154:157], v[216:219], v[2:5]
	v_mfma_f32_16x16x32_bf16 v[54:57], v[150:153], v[182:185], v[54:57]
	v_mfma_f32_16x16x32_bf16 v[50:53], v[158:161], v[182:185], v[50:53]
	v_mfma_f32_16x16x32_bf16 v[38:41], v[150:153], v[196:199], v[38:41]
	v_mfma_f32_16x16x32_bf16 v[34:37], v[158:161], v[196:199], v[34:37]
	v_mfma_f32_16x16x32_bf16 v[22:25], v[150:153], v[204:207], v[22:25]
	v_mfma_f32_16x16x32_bf16 v[18:21], v[158:161], v[204:207], v[18:21]
	v_mfma_f32_16x16x32_bf16 v[6:9], v[150:153], v[220:223], v[6:9]
	v_mfma_f32_16x16x32_bf16 v[2:5], v[158:161], v[220:223], v[2:5]
	s_setprio 0
	s_barrier
	s_cbranch_scc0 .LBB0_1091
	v_readlane_b32 s50, v254, 38
	s_and_b64 vcc, exec, s[16:17]
	v_readlane_b32 s51, v254, 39
	s_cbranch_vccz .LBB0_1094
	s_barrier

.LBB0_1180:
	s_add_u32 s36, s34, 0x100
	s_addc_u32 s37, s35, 0
	s_add_i32 s57, 0, 0x10000
	s_cmpk_eq_i32 s56, 0x7c
	s_cselect_b32 s41, s2, s37
	s_cselect_b32 s40, s3, s36
	s_cselect_b32 s39, s23, s55
	s_cselect_b32 s38, s25, s54
	s_add_i32 s58, 0, 0x14000
	v_add_u32_e32 v78, s57, v233
	v_add_u32_e32 v98, s58, v233
	ds_read_b128 v[66:69], v78
	ds_read_b128 v[70:73], v78 offset:1024
	ds_read_b128 v[74:77], v78 offset:2048
	ds_read_b128 v[78:81], v78 offset:3072
	ds_read_b128 v[82:85], v98
	ds_read_b128 v[86:89], v98 offset:1024
	ds_read_b128 v[94:97], v98 offset:2048
	ds_read_b128 v[98:101], v98 offset:3072
	v_lshl_add_u64 v[200:201], s[34:35], 0, v[196:197]
	s_add_i32 m0, s47, 0xc000
	ds_read_b128 v[162:165], v235
	ds_read_b128 v[166:169], v235 offset:1024
	ds_read_b128 v[170:173], v235 offset:2048
	ds_read_b128 v[174:177], v235 offset:3072
	ds_read_b128 v[178:181], v235 offset:4096
	ds_read_b128 v[182:185], v235 offset:5120
	ds_read_b128 v[186:189], v235 offset:6144
	ds_read_b128 v[190:193], v235 offset:7168
	global_load_lds_dwordx4 v[200:201], off
	v_lshl_add_u64 v[200:201], s[34:35], 0, v[198:199]
	s_add_i32 m0, s47, 0xe000
	s_nop 0
	global_load_lds_dwordx4 v[200:201], off
	s_waitcnt vmcnt(8) lgkmcnt(0)
	s_barrier
	s_setprio 1
	v_mfma_f32_16x16x32_bf16 v[158:161], v[66:69], v[162:165], v[158:161]
	v_mfma_f32_16x16x32_bf16 v[154:157], v[74:77], v[162:165], v[154:157]
	v_mfma_f32_16x16x32_bf16 v[142:145], v[66:69], v[170:173], v[142:145]
	v_mfma_f32_16x16x32_bf16 v[138:141], v[74:77], v[170:173], v[138:141]
	v_mfma_f32_16x16x32_bf16 v[126:129], v[66:69], v[178:181], v[126:129]
	v_mfma_f32_16x16x32_bf16 v[122:125], v[74:77], v[178:181], v[122:125]
	v_mfma_f32_16x16x32_bf16 v[110:113], v[66:69], v[186:189], v[110:113]
	v_mfma_f32_16x16x32_bf16 v[106:109], v[74:77], v[186:189], v[106:109]
	v_mfma_f32_16x16x32_bf16 v[158:161], v[70:73], v[166:169], v[158:161]
	v_mfma_f32_16x16x32_bf16 v[154:157], v[78:81], v[166:169], v[154:157]
	v_mfma_f32_16x16x32_bf16 v[142:145], v[70:73], v[174:177], v[142:145]
	v_mfma_f32_16x16x32_bf16 v[138:141], v[78:81], v[174:177], v[138:141]
	v_mfma_f32_16x16x32_bf16 v[126:129], v[70:73], v[182:185], v[126:129]
	v_mfma_f32_16x16x32_bf16 v[122:125], v[78:81], v[182:185], v[122:125]
	v_mfma_f32_16x16x32_bf16 v[110:113], v[70:73], v[190:193], v[110:113]
	v_mfma_f32_16x16x32_bf16 v[106:109], v[78:81], v[190:193], v[106:109]
	v_mfma_f32_16x16x32_bf16 v[150:153], v[82:85], v[162:165], v[150:153]
	v_mfma_f32_16x16x32_bf16 v[146:149], v[94:97], v[162:165], v[146:149]
	v_mfma_f32_16x16x32_bf16 v[134:137], v[82:85], v[170:173], v[134:137]
	v_mfma_f32_16x16x32_bf16 v[130:133], v[94:97], v[170:173], v[130:133]
	v_mfma_f32_16x16x32_bf16 v[118:121], v[82:85], v[178:181], v[118:121]
	v_mfma_f32_16x16x32_bf16 v[114:117], v[94:97], v[178:181], v[114:117]
	v_mfma_f32_16x16x32_bf16 v[102:105], v[82:85], v[186:189], v[102:105]
	v_mfma_f32_16x16x32_bf16 v[90:93], v[94:97], v[186:189], v[90:93]
	v_mfma_f32_16x16x32_bf16 v[150:153], v[86:89], v[166:169], v[150:153]
	v_mfma_f32_16x16x32_bf16 v[146:149], v[98:101], v[166:169], v[146:149]
	v_mfma_f32_16x16x32_bf16 v[134:137], v[86:89], v[174:177], v[134:137]
	v_mfma_f32_16x16x32_bf16 v[130:133], v[98:101], v[174:177], v[130:133]
	v_mfma_f32_16x16x32_bf16 v[118:121], v[86:89], v[182:185], v[118:121]
	v_mfma_f32_16x16x32_bf16 v[114:117], v[98:101], v[182:185], v[114:117]
	v_mfma_f32_16x16x32_bf16 v[102:105], v[86:89], v[190:193], v[102:105]
	v_mfma_f32_16x16x32_bf16 v[90:93], v[98:101], v[190:193], v[90:93]
	s_setprio 0
	s_barrier
	s_add_i32 s34, s57, s46
	v_lshl_add_u64 v[200:201], s[38:39], 0, v[210:211]
	s_mov_b32 m0, s34
	ds_read_b128 v[162:165], v235 offset:16384
	ds_read_b128 v[166:169], v235 offset:17408
	ds_read_b128 v[170:173], v235 offset:18432
	ds_read_b128 v[174:177], v235 offset:19456
	ds_read_b128 v[178:181], v235 offset:20480
	ds_read_b128 v[182:185], v235 offset:21504
	ds_read_b128 v[186:189], v235 offset:22528
	ds_read_b128 v[190:193], v235 offset:23552
	global_load_lds_dwordx4 v[200:201], off
	s_add_i32 m0, s34, 0x2000
	s_add_u32 s34, s38, 0x200000
	v_lshl_add_u64 v[202:203], s[38:39], 0, v[194:195]
	s_addc_u32 s35, s39, 0
	s_add_i32 s57, s58, s46
	global_load_lds_dwordx4 v[202:203], off
	v_lshl_add_u64 v[204:205], s[34:35], 0, v[210:211]
	s_mov_b32 m0, s57
	v_lshl_add_u64 v[206:207], s[40:41], 0, v[194:195]
	global_load_lds_dwordx4 v[204:205], off
	v_lshl_add_u64 v[204:205], s[34:35], 0, v[194:195]
	s_add_i32 m0, s57, 0x2000
	s_nop 0
	global_load_lds_dwordx4 v[204:205], off
	v_lshl_add_u64 v[204:205], s[40:41], 0, v[210:211]
	s_mov_b32 m0, s47
	s_nop 0
	global_load_lds_dwordx4 v[204:205], off
	s_mov_b32 m0, s48
	s_nop 0
	global_load_lds_dwordx4 v[206:207], off
	s_waitcnt vmcnt(8) lgkmcnt(0)
	s_barrier
	s_setprio 1
	v_mfma_f32_16x16x32_bf16 v[62:65], v[66:69], v[162:165], v[62:65]
	v_mfma_f32_16x16x32_bf16 v[58:61], v[74:77], v[162:165], v[58:61]
	v_mfma_f32_16x16x32_bf16 v[46:49], v[66:69], v[170:173], v[46:49]
	v_mfma_f32_16x16x32_bf16 v[42:45], v[74:77], v[170:173], v[42:45]
	v_mfma_f32_16x16x32_bf16 v[30:33], v[66:69], v[178:181], v[30:33]
	v_mfma_f32_16x16x32_bf16 v[26:29], v[74:77], v[178:181], v[26:29]
	v_mfma_f32_16x16x32_bf16 v[14:17], v[66:69], v[186:189], v[14:17]
	v_mfma_f32_16x16x32_bf16 v[10:13], v[74:77], v[186:189], v[10:13]
	v_mfma_f32_16x16x32_bf16 v[62:65], v[70:73], v[166:169], v[62:65]
	v_mfma_f32_16x16x32_bf16 v[58:61], v[78:81], v[166:169], v[58:61]
	v_mfma_f32_16x16x32_bf16 v[46:49], v[70:73], v[174:177], v[46:49]
	v_mfma_f32_16x16x32_bf16 v[42:45], v[78:81], v[174:177], v[42:45]
	v_mfma_f32_16x16x32_bf16 v[30:33], v[70:73], v[182:185], v[30:33]
	v_mfma_f32_16x16x32_bf16 v[26:29], v[78:81], v[182:185], v[26:29]
	v_mfma_f32_16x16x32_bf16 v[14:17], v[70:73], v[190:193], v[14:17]
	v_mfma_f32_16x16x32_bf16 v[10:13], v[78:81], v[190:193], v[10:13]
	v_mfma_f32_16x16x32_bf16 v[54:57], v[82:85], v[162:165], v[54:57]
	v_mfma_f32_16x16x32_bf16 v[50:53], v[94:97], v[162:165], v[50:53]
	v_mfma_f32_16x16x32_bf16 v[38:41], v[82:85], v[170:173], v[38:41]
	v_mfma_f32_16x16x32_bf16 v[34:37], v[94:97], v[170:173], v[34:37]
	v_mfma_f32_16x16x32_bf16 v[22:25], v[82:85], v[178:181], v[22:25]
	v_mfma_f32_16x16x32_bf16 v[18:21], v[94:97], v[178:181], v[18:21]
	v_mfma_f32_16x16x32_bf16 v[6:9], v[82:85], v[186:189], v[6:9]
	v_mfma_f32_16x16x32_bf16 v[2:5], v[94:97], v[186:189], v[2:5]
	v_mfma_f32_16x16x32_bf16 v[54:57], v[86:89], v[166:169], v[54:57]
	v_mfma_f32_16x16x32_bf16 v[50:53], v[98:101], v[166:169], v[50:53]
	v_mfma_f32_16x16x32_bf16 v[38:41], v[86:89], v[174:177], v[38:41]
	v_mfma_f32_16x16x32_bf16 v[34:37], v[98:101], v[174:177], v[34:37]
	v_mfma_f32_16x16x32_bf16 v[22:25], v[86:89], v[182:185], v[22:25]
	v_mfma_f32_16x16x32_bf16 v[18:21], v[98:101], v[182:185], v[18:21]
	v_mfma_f32_16x16x32_bf16 v[6:9], v[86:89], v[190:193], v[6:9]
	v_mfma_f32_16x16x32_bf16 v[2:5], v[98:101], v[190:193], v[2:5]
	s_setprio 0
	s_barrier
	s_add_i32 s57, 0, 0x18000
	s_add_i32 s58, 0, 0x1c000
	v_add_u32_e32 v78, s57, v233
	v_add_u32_e32 v98, s58, v233
	ds_read_b128 v[66:69], v78
	ds_read_b128 v[70:73], v78 offset:1024
	ds_read_b128 v[74:77], v78 offset:2048
	ds_read_b128 v[78:81], v78 offset:3072
	ds_read_b128 v[82:85], v98
	ds_read_b128 v[86:89], v98 offset:1024
	ds_read_b128 v[94:97], v98 offset:2048
	ds_read_b128 v[98:101], v98 offset:3072
	s_add_u32 s34, s40, 0x200000
	s_addc_u32 s35, s41, 0
	s_mov_b32 m0, s49
	v_lshl_add_u64 v[208:209], s[34:35], 0, v[210:211]
	ds_read_b128 v[162:165], v235 offset:32768
	ds_read_b128 v[166:169], v235 offset:33792
	ds_read_b128 v[170:173], v235 offset:34816
	ds_read_b128 v[174:177], v235 offset:35840
	ds_read_b128 v[178:181], v235 offset:36864
	ds_read_b128 v[182:185], v235 offset:37888
	ds_read_b128 v[186:189], v235 offset:38912
	ds_read_b128 v[190:193], v235 offset:39936
	global_load_lds_dwordx4 v[208:209], off
	v_lshl_add_u64 v[208:209], s[34:35], 0, v[194:195]
	s_mov_b32 m0, s50
	s_nop 0
	global_load_lds_dwordx4 v[208:209], off
	s_waitcnt vmcnt(8) lgkmcnt(0)
	s_barrier
	s_setprio 1
	v_mfma_f32_16x16x32_bf16 v[158:161], v[66:69], v[162:165], v[158:161]
	v_mfma_f32_16x16x32_bf16 v[154:157], v[74:77], v[162:165], v[154:157]
	v_mfma_f32_16x16x32_bf16 v[142:145], v[66:69], v[170:173], v[142:145]
	v_mfma_f32_16x16x32_bf16 v[138:141], v[74:77], v[170:173], v[138:141]
	v_mfma_f32_16x16x32_bf16 v[126:129], v[66:69], v[178:181], v[126:129]
	v_mfma_f32_16x16x32_bf16 v[122:125], v[74:77], v[178:181], v[122:125]
	v_mfma_f32_16x16x32_bf16 v[110:113], v[66:69], v[186:189], v[110:113]
	v_mfma_f32_16x16x32_bf16 v[106:109], v[74:77], v[186:189], v[106:109]
	v_mfma_f32_16x16x32_bf16 v[158:161], v[70:73], v[166:169], v[158:161]
	v_mfma_f32_16x16x32_bf16 v[154:157], v[78:81], v[166:169], v[154:157]
	v_mfma_f32_16x16x32_bf16 v[142:145], v[70:73], v[174:177], v[142:145]
	v_mfma_f32_16x16x32_bf16 v[138:141], v[78:81], v[174:177], v[138:141]
	v_mfma_f32_16x16x32_bf16 v[126:129], v[70:73], v[182:185], v[126:129]
	v_mfma_f32_16x16x32_bf16 v[122:125], v[78:81], v[182:185], v[122:125]
	v_mfma_f32_16x16x32_bf16 v[110:113], v[70:73], v[190:193], v[110:113]
	v_mfma_f32_16x16x32_bf16 v[106:109], v[78:81], v[190:193], v[106:109]
	v_mfma_f32_16x16x32_bf16 v[150:153], v[82:85], v[162:165], v[150:153]
	v_mfma_f32_16x16x32_bf16 v[146:149], v[94:97], v[162:165], v[146:149]
	v_mfma_f32_16x16x32_bf16 v[134:137], v[82:85], v[170:173], v[134:137]
	v_mfma_f32_16x16x32_bf16 v[130:133], v[94:97], v[170:173], v[130:133]
	v_mfma_f32_16x16x32_bf16 v[118:121], v[82:85], v[178:181], v[118:121]
	v_mfma_f32_16x16x32_bf16 v[114:117], v[94:97], v[178:181], v[114:117]
	v_mfma_f32_16x16x32_bf16 v[102:105], v[82:85], v[186:189], v[102:105]
	v_mfma_f32_16x16x32_bf16 v[90:93], v[94:97], v[186:189], v[90:93]
	v_mfma_f32_16x16x32_bf16 v[150:153], v[86:89], v[166:169], v[150:153]
	v_mfma_f32_16x16x32_bf16 v[146:149], v[98:101], v[166:169], v[146:149]
	v_mfma_f32_16x16x32_bf16 v[134:137], v[86:89], v[174:177], v[134:137]
	v_mfma_f32_16x16x32_bf16 v[130:133], v[98:101], v[174:177], v[130:133]
	v_mfma_f32_16x16x32_bf16 v[118:121], v[86:89], v[182:185], v[118:121]
	v_mfma_f32_16x16x32_bf16 v[114:117], v[98:101], v[182:185], v[114:117]
	v_mfma_f32_16x16x32_bf16 v[102:105], v[86:89], v[190:193], v[102:105]
	v_mfma_f32_16x16x32_bf16 v[90:93], v[98:101], v[190:193], v[90:93]
	s_setprio 0
	s_barrier
	s_add_i32 s34, s57, s46
	v_lshl_add_u64 v[200:201], v[200:201], 0, s[64:65]
	s_mov_b32 m0, s34
	ds_read_b128 v[162:165], v235 offset:49152
	ds_read_b128 v[166:169], v235 offset:50176
	ds_read_b128 v[170:173], v235 offset:51200
	ds_read_b128 v[174:177], v235 offset:52224
	ds_read_b128 v[178:181], v235 offset:53248
	ds_read_b128 v[182:185], v235 offset:54272
	ds_read_b128 v[186:189], v235 offset:55296
	ds_read_b128 v[190:193], v235 offset:56320
	global_load_lds_dwordx4 v[200:201], off
	s_add_i32 m0, s34, 0x2000
	s_add_u32 s34, s38, 0x200080
	v_lshl_add_u64 v[200:201], v[202:203], 0, s[64:65]
	s_addc_u32 s35, s39, 0
	s_add_i32 s38, s58, s46
	global_load_lds_dwordx4 v[200:201], off
	v_lshl_add_u64 v[200:201], s[34:35], 0, v[210:211]
	s_mov_b32 m0, s38
	s_nop 0
	global_load_lds_dwordx4 v[200:201], off
	v_lshl_add_u64 v[200:201], s[34:35], 0, v[194:195]
	s_add_i32 m0, s38, 0x2000
	s_nop 0
	global_load_lds_dwordx4 v[200:201], off
	v_lshl_add_u64 v[200:201], v[204:205], 0, s[64:65]
	s_mov_b32 m0, s51
	s_nop 0
	global_load_lds_dwordx4 v[200:201], off
	v_lshl_add_u64 v[200:201], v[206:207], 0, s[64:65]
	s_mov_b32 m0, s52
	s_nop 0
	global_load_lds_dwordx4 v[200:201], off
	s_add_i32 s56, s56, 2
	s_add_u32 s54, s54, 0x100
	s_addc_u32 s55, s55, 0
	s_cmpk_gt_u32 s56, 0x7d
	s_mov_b64 s[34:35], s[36:37]
	s_waitcnt vmcnt(8) lgkmcnt(0)
	s_barrier
	s_setprio 1
	v_mfma_f32_16x16x32_bf16 v[62:65], v[66:69], v[162:165], v[62:65]
	v_mfma_f32_16x16x32_bf16 v[58:61], v[74:77], v[162:165], v[58:61]
	v_mfma_f32_16x16x32_bf16 v[46:49], v[66:69], v[170:173], v[46:49]
	v_mfma_f32_16x16x32_bf16 v[42:45], v[74:77], v[170:173], v[42:45]
	v_mfma_f32_16x16x32_bf16 v[30:33], v[66:69], v[178:181], v[30:33]
	v_mfma_f32_16x16x32_bf16 v[26:29], v[74:77], v[178:181], v[26:29]
	v_mfma_f32_16x16x32_bf16 v[14:17], v[66:69], v[186:189], v[14:17]
	v_mfma_f32_16x16x32_bf16 v[10:13], v[74:77], v[186:189], v[10:13]
	v_mfma_f32_16x16x32_bf16 v[62:65], v[70:73], v[166:169], v[62:65]
	v_mfma_f32_16x16x32_bf16 v[58:61], v[78:81], v[166:169], v[58:61]
	v_mfma_f32_16x16x32_bf16 v[46:49], v[70:73], v[174:177], v[46:49]
	v_mfma_f32_16x16x32_bf16 v[42:45], v[78:81], v[174:177], v[42:45]
	v_mfma_f32_16x16x32_bf16 v[30:33], v[70:73], v[182:185], v[30:33]
	v_mfma_f32_16x16x32_bf16 v[26:29], v[78:81], v[182:185], v[26:29]
	v_mfma_f32_16x16x32_bf16 v[14:17], v[70:73], v[190:193], v[14:17]
	v_mfma_f32_16x16x32_bf16 v[10:13], v[78:81], v[190:193], v[10:13]
	v_mfma_f32_16x16x32_bf16 v[54:57], v[82:85], v[162:165], v[54:57]
	v_mfma_f32_16x16x32_bf16 v[50:53], v[94:97], v[162:165], v[50:53]
	v_mfma_f32_16x16x32_bf16 v[38:41], v[82:85], v[170:173], v[38:41]
	v_mfma_f32_16x16x32_bf16 v[34:37], v[94:97], v[170:173], v[34:37]
	v_mfma_f32_16x16x32_bf16 v[22:25], v[82:85], v[178:181], v[22:25]
	v_mfma_f32_16x16x32_bf16 v[18:21], v[94:97], v[178:181], v[18:21]
	v_mfma_f32_16x16x32_bf16 v[6:9], v[82:85], v[186:189], v[6:9]
	v_mfma_f32_16x16x32_bf16 v[2:5], v[94:97], v[186:189], v[2:5]
	v_mfma_f32_16x16x32_bf16 v[54:57], v[86:89], v[166:169], v[54:57]
	v_mfma_f32_16x16x32_bf16 v[50:53], v[98:101], v[166:169], v[50:53]
	v_mfma_f32_16x16x32_bf16 v[38:41], v[86:89], v[174:177], v[38:41]
	v_mfma_f32_16x16x32_bf16 v[34:37], v[98:101], v[174:177], v[34:37]
	v_mfma_f32_16x16x32_bf16 v[22:25], v[86:89], v[182:185], v[22:25]
	v_mfma_f32_16x16x32_bf16 v[18:21], v[98:101], v[182:185], v[18:21]
	v_mfma_f32_16x16x32_bf16 v[6:9], v[86:89], v[190:193], v[6:9]
	v_mfma_f32_16x16x32_bf16 v[2:5], v[98:101], v[190:193], v[2:5]
	s_setprio 0
	s_barrier
	s_cbranch_scc0 .LBB0_1180
	s_and_b64 vcc, exec, s[20:21]
	s_cbranch_vccz .LBB0_1183
	s_barrier
